# M1 and M3 GLA units: global loads de-serialized (d16_hi loads, hoisted gate-row loads, deferred unpack), one wait per item
# speedup vs baseline: 1.0458x; 1.0458x over previous
; template <bool FINAL>
; DI void gla_unit(KA a, int l, int item, LAS unsigned char* lds) {
;     ...
; #pragma unroll
;     for (int hh = 0; hh < 2; ++hh) {
;         const int hd = 2 * hp + hh;
; #pragma unroll
;         for (int jj = 0; jj < 8; ++jj) {
;             const int t = 8 * tg + jj; kraw[hh][jj] = 0u; qraw[hh][jj] = 0u;
;             if (t < nvalid) { kraw[hh][jj] = U[(size_t)(row0 + t) * UN + U_K + hd * 64 + dk]; if (FINAL) qraw[hh][jj] = U[(size_t)(row0 + t) * UN + U_Q + hd * 64 + dk]; }
;         }
.LBB0_607:
	v_mov_b32_e32 v107, v212
	s_load_dwordx2 s[28:29], s[2:3], 0xd8
	v_readfirstlane_b32 s48, v107
	s_and_b32 s17, s33, 1
	s_ashr_i32 s47, s48, 6
	v_and_b32_e32 v75, 63, v107
	s_waitcnt lgkmcnt(0)
	s_add_u32 s34, s28, 0x5000000
	s_addc_u32 s35, s29, 0
	s_lshl_b32 s59, s47, 3
	s_lshl_b32 s60, s17, 7
	s_cmp_lt_i32 s59, s0
	s_cselect_b64 s[8:9], -1, 0
	v_mov_b32_e32 v90, 0
	s_and_b64 vcc, exec, s[8:9]
	v_lshlrev_b32_e32 v8, 1, v75
	v_mov_b32_e32 v93, 0
	s_cbranch_vccz .LBB0_609
	s_add_i32 s6, s59, s51
	s_mul_hi_i32 s7, s6, 0x1600
	s_mulk_i32 s6, 0x1600
	s_add_u32 s6, s34, s6
	s_addc_u32 s7, s35, s7
	s_lshl_b32 s10, s60, 1
	s_add_u32 s6, s6, s10
	s_addc_u32 s7, s7, 0
	global_load_short_d16_hi v93, v8, s[6:7] offset:2560
.LBB0_609:
	s_or_b32 s58, s59, 1
	s_cmp_lt_i32 s58, s0
	s_cselect_b64 s[10:11], -1, 0
	s_cmp_ge_i32 s58, s0
	s_cbranch_scc1 .LBB0_611
	s_add_i32 s6, s58, s51
	s_mul_hi_i32 s7, s6, 0x1600
	s_mulk_i32 s6, 0x1600
	s_add_u32 s6, s34, s6
	s_addc_u32 s7, s35, s7
	s_lshl_b32 s12, s60, 1
	s_add_u32 s6, s6, s12
	s_addc_u32 s7, s7, 0
	global_load_short_d16_hi v90, v8, s[6:7] offset:2560
.LBB0_611:
	s_or_b32 s57, s59, 2
	s_cmp_lt_i32 s57, s0
	v_mov_b32_e32 v99, 0
	s_cselect_b64 s[12:13], -1, 0
	s_cmp_ge_i32 s57, s0
	v_mov_b32_e32 v100, 0
	s_cbranch_scc1 .LBB0_613
	s_add_i32 s6, s57, s51
	s_mul_hi_i32 s7, s6, 0x1600
	s_mulk_i32 s6, 0x1600
	s_add_u32 s6, s34, s6
	s_addc_u32 s7, s35, s7
	s_lshl_b32 s14, s60, 1
	s_add_u32 s6, s6, s14
	s_addc_u32 s7, s7, 0
	global_load_short_d16_hi v100, v8, s[6:7] offset:2560
.LBB0_613:
	s_or_b32 s56, s59, 3
	s_cmp_lt_i32 s56, s0
	s_cselect_b64 s[14:15], -1, 0
	s_cmp_ge_i32 s56, s0
	s_cbranch_scc1 .LBB0_615
	s_add_i32 s6, s56, s51
	s_mul_hi_i32 s7, s6, 0x1600
	s_mulk_i32 s6, 0x1600
	s_add_u32 s6, s34, s6
	s_addc_u32 s7, s35, s7
	s_lshl_b32 s18, s60, 1
	s_add_u32 s6, s6, s18
	s_addc_u32 s7, s7, 0
	global_load_short_d16_hi v99, v8, s[6:7] offset:2560
.LBB0_615:
	s_or_b32 s55, s59, 4
	s_cmp_lt_i32 s55, s0
	v_mov_b32_e32 v102, 0
	s_cselect_b64 s[36:37], -1, 0
	s_cmp_ge_i32 s55, s0
	v_mov_b32_e32 v104, 0
	s_cbranch_scc1 .LBB0_617
	s_add_i32 s6, s55, s51
	s_mul_hi_i32 s7, s6, 0x1600
	s_mulk_i32 s6, 0x1600
	s_add_u32 s6, s34, s6
	s_addc_u32 s7, s35, s7
	s_lshl_b32 s18, s60, 1
	s_add_u32 s6, s6, s18
	s_addc_u32 s7, s7, 0
	global_load_short_d16_hi v104, v8, s[6:7] offset:2560
.LBB0_617:
	s_or_b32 s54, s59, 5
	s_cmp_lt_i32 s54, s0
	s_cselect_b64 s[38:39], -1, 0
	s_cmp_ge_i32 s54, s0
	s_cbranch_scc1 .LBB0_619
	s_add_i32 s6, s54, s51
	s_mul_hi_i32 s7, s6, 0x1600
	s_mulk_i32 s6, 0x1600
	s_add_u32 s6, s34, s6
	s_addc_u32 s7, s35, s7
	s_lshl_b32 s18, s60, 1
	s_add_u32 s6, s6, s18
	s_addc_u32 s7, s7, 0
	global_load_short_d16_hi v102, v8, s[6:7] offset:2560
.LBB0_619:
	s_or_b32 s53, s59, 6
	s_cmp_lt_i32 s53, s0
	v_mov_b32_e32 v105, 0
	s_cselect_b64 s[40:41], -1, 0
	s_cmp_ge_i32 s53, s0
	v_mov_b32_e32 v106, 0
	s_cbranch_scc1 .LBB0_621
	s_add_i32 s6, s53, s51
	s_mul_hi_i32 s7, s6, 0x1600
	s_mulk_i32 s6, 0x1600
	s_add_u32 s6, s34, s6
	s_addc_u32 s7, s35, s7
	s_lshl_b32 s18, s60, 1
	s_add_u32 s6, s6, s18
	s_addc_u32 s7, s7, 0
	global_load_short_d16_hi v106, v8, s[6:7] offset:2560
.LBB0_621:
	s_or_b32 s52, s59, 7
	s_cmp_lt_i32 s52, s0
	s_cselect_b64 s[42:43], -1, 0
	s_cmp_ge_i32 s52, s0
	s_cbranch_scc1 .LBB0_623
	s_add_i32 s6, s52, s51
	s_mul_hi_i32 s7, s6, 0x1600
	s_mulk_i32 s6, 0x1600
	s_add_u32 s6, s34, s6
	s_addc_u32 s7, s35, s7
	s_lshl_b32 s18, s60, 1
	s_add_u32 s6, s6, s18
	s_addc_u32 s7, s7, 0
	global_load_short_d16_hi v105, v8, s[6:7] offset:2560

; template <bool FINAL>
; DI void gla_unit(KA a, int l, int item, LAS unsigned char* lds) {
;     ...
;     for (int hh = 0; hh < 2; ++hh) {
;         const int hd = 2 * hp + hh;
; #pragma unroll
;         for (int jj = 0; jj < 8; ++jj) {
;             const int t = 8 * tg + jj; kraw[hh][jj] = 0u; qraw[hh][jj] = 0u;
;             if (t < nvalid) { kraw[hh][jj] = U[(size_t)(row0 + t) * UN + U_K + hd * 64 + dk]; if (FINAL) qraw[hh][jj] = U[(size_t)(row0 + t) * UN + U_Q + hd * 64 + dk]; }
;         }
.LBB0_627:
	s_or_b32 s46, s49, 1
	v_cndmask_b32_e64 v9, 0, 1, s[8:9]
	s_lshl_b32 s0, s46, 6
	v_mov_b32_e32 v89, 0
	v_cmp_ne_u32_e64 s[22:23], 1, v9
	s_andn2_b64 vcc, exec, s[8:9]
	v_mov_b32_e32 v95, 0
	s_cbranch_vccnz .LBB0_629
	s_add_i32 s8, s59, s51
	s_mul_hi_i32 s9, s8, 0x1600
	s_mulk_i32 s8, 0x1600
	s_add_u32 s8, s34, s8
	s_addc_u32 s9, s35, s9
	s_lshl_b32 s16, s0, 1
	s_add_u32 s8, s8, s16
	s_addc_u32 s9, s9, 0
	global_load_short_d16_hi v95, v8, s[8:9] offset:2560
.LBB0_629:
	v_cndmask_b32_e64 v9, 0, 1, s[10:11]
	v_cmp_ne_u32_e64 s[20:21], 1, v9
	s_andn2_b64 vcc, exec, s[10:11]
	s_cbranch_vccnz .LBB0_631
	s_add_i32 s8, s58, s51
	s_mul_hi_i32 s9, s8, 0x1600
	s_mulk_i32 s8, 0x1600
	s_add_u32 s8, s34, s8
	s_addc_u32 s9, s35, s9
	s_lshl_b32 s10, s0, 1
	s_add_u32 s8, s8, s10
	s_addc_u32 s9, s9, 0
	global_load_short_d16_hi v89, v8, s[8:9] offset:2560
.LBB0_631:
	v_cndmask_b32_e64 v9, 0, 1, s[12:13]
	v_mov_b32_e32 v91, 0
	v_cmp_ne_u32_e64 s[18:19], 1, v9
	s_andn2_b64 vcc, exec, s[12:13]
	v_mov_b32_e32 v97, 0
	s_cbranch_vccnz .LBB0_633
	s_add_i32 s8, s57, s51
	s_mul_hi_i32 s9, s8, 0x1600
	s_mulk_i32 s8, 0x1600
	s_add_u32 s8, s34, s8
	s_addc_u32 s9, s35, s9
	s_lshl_b32 s10, s0, 1
	s_add_u32 s8, s8, s10
	s_addc_u32 s9, s9, 0
	global_load_short_d16_hi v97, v8, s[8:9] offset:2560
.LBB0_633:
	v_cndmask_b32_e64 v9, 0, 1, s[14:15]
	v_cmp_ne_u32_e64 s[16:17], 1, v9
	s_andn2_b64 vcc, exec, s[14:15]
	s_cbranch_vccnz .LBB0_635
	s_add_i32 s8, s56, s51
	s_mul_hi_i32 s9, s8, 0x1600
	s_mulk_i32 s8, 0x1600
	s_add_u32 s8, s34, s8
	s_addc_u32 s9, s35, s9
	s_lshl_b32 s10, s0, 1
	s_add_u32 s8, s8, s10
	s_addc_u32 s9, s9, 0
	global_load_short_d16_hi v91, v8, s[8:9] offset:2560
.LBB0_635:
	v_cndmask_b32_e64 v9, 0, 1, s[36:37]
	v_mov_b32_e32 v92, 0
	v_cmp_ne_u32_e64 s[14:15], 1, v9
	s_andn2_b64 vcc, exec, s[36:37]
	v_mov_b32_e32 v98, 0
	s_cbranch_vccnz .LBB0_637
	s_add_i32 s8, s55, s51
	s_mul_hi_i32 s9, s8, 0x1600
	s_mulk_i32 s8, 0x1600
	s_add_u32 s8, s34, s8
	s_addc_u32 s9, s35, s9
	s_lshl_b32 s10, s0, 1
	s_add_u32 s8, s8, s10
	s_addc_u32 s9, s9, 0
	global_load_short_d16_hi v98, v8, s[8:9] offset:2560
.LBB0_637:
	v_cndmask_b32_e64 v9, 0, 1, s[38:39]
	v_cmp_ne_u32_e64 s[12:13], 1, v9
	s_andn2_b64 vcc, exec, s[38:39]
	s_cbranch_vccnz .LBB0_639
	s_add_i32 s8, s54, s51
	s_mul_hi_i32 s9, s8, 0x1600
	s_mulk_i32 s8, 0x1600
	s_add_u32 s8, s34, s8
	s_addc_u32 s9, s35, s9
	s_lshl_b32 s10, s0, 1
	s_add_u32 s8, s8, s10
	s_addc_u32 s9, s9, 0
	global_load_short_d16_hi v92, v8, s[8:9] offset:2560
.LBB0_639:
	v_cndmask_b32_e64 v9, 0, 1, s[40:41]
	v_mov_b32_e32 v94, 0
	v_cmp_ne_u32_e64 s[10:11], 1, v9
	s_andn2_b64 vcc, exec, s[40:41]
	v_mov_b32_e32 v101, 0
	s_cbranch_vccnz .LBB0_641
	s_add_i32 s8, s53, s51
	s_mul_hi_i32 s9, s8, 0x1600
	s_mulk_i32 s8, 0x1600
	s_add_u32 s8, s34, s8
	s_addc_u32 s9, s35, s9
	s_lshl_b32 s36, s0, 1
	s_add_u32 s8, s8, s36
	s_addc_u32 s9, s9, 0
	global_load_short_d16_hi v101, v8, s[8:9] offset:2560
.LBB0_641:
	v_cndmask_b32_e64 v9, 0, 1, s[42:43]
	v_cmp_ne_u32_e64 s[8:9], 1, v9
	s_andn2_b64 vcc, exec, s[42:43]
	s_cbranch_vccnz .LBB0_643
	s_add_i32 s36, s52, s51
	s_mul_hi_i32 s37, s36, 0x1600
	s_mulk_i32 s36, 0x1600
	s_add_u32 s36, s34, s36
	s_addc_u32 s37, s35, s37
	s_lshl_b32 s0, s0, 1
	s_add_u32 s36, s36, s0
	s_addc_u32 s37, s37, 0
	global_load_short_d16_hi v94, v8, s[36:37] offset:2560

; template <bool FINAL>
; DI void gla_unit(KA a, int l, int item, LAS unsigned char* lds) {
;     ...
;     {
;         float wg[2][16], bg[2];
; #pragma unroll
;         for (int hh = 0; hh < 2; ++hh) {
;             const float* wg2 = a->in[18] + (size_t)l * 16 * 256 + (2 * hp + hh) * 64 + dk;
; #pragma unroll
;             for (int e = 0; e < 16; ++e) wg[hh][e] = wg2[e * 256];
;             bg[hh] = a->in[19][l * 256 + (2 * hp + hh) * 64 + dk];
;         }
;         float run0 = 0.f, run1 = 0.f;
; #pragma unroll
;         for (int jj = 0; jj < 8; ++jj) {
;             const int t = 8 * tg + jj;
;             float ga = 0.f, gb = 0.f;
;             if (t < nvalid) {
;                 const u32x4* lp = (const u32x4*)(U + (size_t)(row0 + t) * UN + U_LR);
;                 float lr[16]; unpack8(lp[0], lr); unpack8(lp[1], lr + 8);
.LBB0_649:
	s_load_dwordx4 s[4:7], s[2:3], 0x90
	v_readlane_b32 s24, v255, 1
	v_readlane_b32 s25, v255, 2
	s_lshl_b64 s[24:25], s[24:25], 2
	v_lshlrev_b32_e32 v144, 2, v75
	s_waitcnt lgkmcnt(0)
	s_add_u32 s4, s4, s24
	s_addc_u32 s5, s5, s25
	v_readlane_b32 s0, v255, 3
	v_lshl_add_u64 v[16:17], s[4:5], 0, v[144:145]
	v_mov_b32_e32 v29, v145
	v_or_b32_e32 v44, s0, v75
	s_lshl_b32 s0, s60, 2
	v_lshl_add_u64 v[16:17], v[16:17], 0, s[0:1]
	s_movk_i32 s0, 0x1000
	v_add_co_u32_e32 v18, vcc, s0, v16
	s_movk_i32 s0, 0x2000
	s_nop 0
	v_addc_co_u32_e32 v19, vcc, 0, v17, vcc
	v_add_co_u32_e32 v20, vcc, s0, v16
	s_movk_i32 s0, 0x3000
	s_nop 0
	v_addc_co_u32_e32 v21, vcc, 0, v17, vcc
	v_add_co_u32_e32 v42, vcc, s0, v16
	v_or_b32_e32 v28, s60, v44
	s_nop 0
	v_addc_co_u32_e32 v43, vcc, 0, v17, vcc
	v_lshl_add_u64 v[28:29], v[28:29], 2, s[6:7]
	global_load_dword v112, v[16:17], off
	global_load_dword v111, v[16:17], off offset:1024
	global_load_dword v110, v[16:17], off offset:2048
	global_load_dword v109, v[16:17], off offset:3072
	global_load_dword v115, v[20:21], off offset:-4096
	global_load_dword v114, v[18:19], off offset:1024
	global_load_dword v33, v[18:19], off offset:2048
	global_load_dword v32, v[18:19], off offset:3072
	global_load_dword v31, v[20:21], off
	global_load_dword v30, v[20:21], off offset:1024
	global_load_dword v27, v[20:21], off offset:2048
	global_load_dword v26, v[20:21], off offset:3072
	global_load_dword v25, v[42:43], off
	global_load_dword v24, v[42:43], off offset:1024
	global_load_dword v23, v[42:43], off offset:2048
	global_load_dword v22, v[42:43], off offset:3072
	global_load_dword v113, v[28:29], off
	global_load_dword v118, v[16:17], off offset:256
	global_load_dword v117, v[16:17], off offset:1280
	global_load_dword v116, v[16:17], off offset:2304
	global_load_dword v121, v[16:17], off offset:3328
	global_load_dword v120, v[18:19], off offset:256
	global_load_dword v119, v[18:19], off offset:1280
	global_load_dword v41, v[18:19], off offset:2304
	global_load_dword v40, v[18:19], off offset:3328
	global_load_dword v39, v[20:21], off offset:256
	global_load_dword v38, v[20:21], off offset:1280
	global_load_dword v37, v[20:21], off offset:2304
	global_load_dword v36, v[20:21], off offset:3328
	global_load_dword v35, v[42:43], off offset:256
	global_load_dword v34, v[42:43], off offset:1280
	global_load_dword v29, v[42:43], off offset:2304
	global_load_dword v28, v[42:43], off offset:3328
	v_add_u32_e32 v16, s60, v44
	v_mov_b32_e32 v17, v145
	v_lshl_add_u64 v[16:17], v[16:17], 2, s[6:7]
	global_load_dword v122, v[16:17], off offset:256
	s_and_b64 vcc, exec, s[22:23]
	s_cbranch_vccnz .Lpf_m1_0
	s_add_i32 s0, s59, s51
	s_mul_hi_i32 s5, s0, 0x1600
	s_mulk_i32 s0, 0x1600
	s_add_u32 s4, s34, s0
	s_addc_u32 s5, s35, s5
	global_load_dwordx4 v[128:131], v213, s[4:5] offset:1024
	global_load_dwordx4 v[132:135], v213, s[4:5] offset:1040
.Lpf_m1_0:
	s_and_b64 vcc, exec, s[20:21]
	s_cbranch_vccnz .Lpf_m1_1
	s_add_i32 s0, s58, s51
	s_mul_hi_i32 s5, s0, 0x1600
	s_mulk_i32 s0, 0x1600
	s_add_u32 s4, s34, s0
	s_addc_u32 s5, s35, s5
	global_load_dwordx4 v[136:139], v213, s[4:5] offset:1024
	global_load_dwordx4 v[140:143], v213, s[4:5] offset:1040
.Lpf_m1_1:
	s_and_b64 vcc, exec, s[18:19]
	s_cbranch_vccnz .Lpf_m1_2
	s_add_i32 s0, s57, s51
	s_mul_hi_i32 s5, s0, 0x1600
	s_mulk_i32 s0, 0x1600
	s_add_u32 s4, s34, s0
	s_addc_u32 s5, s35, s5
	global_load_dwordx4 v[154:157], v213, s[4:5] offset:1024
	global_load_dwordx4 v[158:161], v213, s[4:5] offset:1040
.Lpf_m1_2:
	s_and_b64 vcc, exec, s[16:17]
	s_cbranch_vccnz .Lpf_m1_3
	s_add_i32 s0, s56, s51
	s_mul_hi_i32 s5, s0, 0x1600
	s_mulk_i32 s0, 0x1600
	s_add_u32 s4, s34, s0
	s_addc_u32 s5, s35, s5
	global_load_dwordx4 v[162:165], v213, s[4:5] offset:1024
	global_load_dwordx4 v[166:169], v213, s[4:5] offset:1040
.Lpf_m1_3:
	s_and_b64 vcc, exec, s[14:15]
	s_cbranch_vccnz .Lpf_m1_4
	s_add_i32 s0, s55, s51
	s_mul_hi_i32 s5, s0, 0x1600
	s_mulk_i32 s0, 0x1600
	s_add_u32 s4, s34, s0
	s_addc_u32 s5, s35, s5
	global_load_dwordx4 v[172:175], v213, s[4:5] offset:1024
	global_load_dwordx4 v[176:179], v213, s[4:5] offset:1040
.Lpf_m1_4:
	s_and_b64 vcc, exec, s[12:13]
	s_cbranch_vccnz .Lpf_m1_5
	s_add_i32 s0, s54, s51
	s_mul_hi_i32 s5, s0, 0x1600
	s_mulk_i32 s0, 0x1600
	s_add_u32 s4, s34, s0
	s_addc_u32 s5, s35, s5
	global_load_dwordx4 v[180:183], v213, s[4:5] offset:1024
	global_load_dwordx4 v[184:187], v213, s[4:5] offset:1040
.Lpf_m1_5:
	s_and_b64 vcc, exec, s[10:11]
	s_cbranch_vccnz .Lpf_m1_6
	s_add_i32 s0, s53, s51
	s_mul_hi_i32 s5, s0, 0x1600
	s_mulk_i32 s0, 0x1600
	s_add_u32 s4, s34, s0
	s_addc_u32 s5, s35, s5
	global_load_dwordx4 v[188:191], v213, s[4:5] offset:1024
	global_load_dwordx4 v[192:195], v213, s[4:5] offset:1040
.Lpf_m1_6:
	s_and_b64 vcc, exec, s[8:9]
	s_cbranch_vccnz .Lpf_m1_7
	s_add_i32 s0, s52, s51
	s_mul_hi_i32 s5, s0, 0x1600
	s_mulk_i32 s0, 0x1600
	s_add_u32 s4, s34, s0
	s_addc_u32 s5, s35, s5
	global_load_dwordx4 v[196:199], v213, s[4:5] offset:1024
	global_load_dwordx4 v[200:203], v213, s[4:5] offset:1040
; template <bool FINAL>
; DI void gla_unit(KA a, int l, int item, LAS unsigned char* lds) {
;     ...
;         for (int jj = 0; jj < 8; ++jj) {
;             const int t = 8 * tg + jj;
;             float ga = 0.f, gb = 0.f;
;             if (t < nvalid) {
;                 const u32x4* lp = (const u32x4*)(U + (size_t)(row0 + t) * UN + U_LR);
;                 float lr[16]; unpack8(lp[0], lr); unpack8(lp[1], lr + 8);
;                 float za = bg[0], zb = bg[1];
; #pragma unroll
;                 for (int e = 0; e < 16; ++e) { za += wg[0][e] * lr[e]; zb += wg[1][e] * lr[e]; }
;                 ga = (fminf(za, 0.f) - __logf(1.f + __expf(-fabsf(za)))) * (1.f / 16.f);
;                 gb = (fminf(zb, 0.f) - __logf(1.f + __expf(-fabsf(zb)))) * (1.f / 16.f);
;             }
;             run0 += ga; run1 += gb; bl[0][jj] = run0; bl[1][jj] = run1;
;         }
.Lpf_m1_7:
	v_mov_b32_e32 v42, 0
	s_and_b64 vcc, exec, s[22:23]
	v_mov_b32_e32 v20, 0
	v_mov_b32_e32 v21, 0
	s_cbranch_vccnz .LBB0_651
	s_add_i32 s0, s59, s51
	s_mul_hi_i32 s5, s0, 0x1600
	s_mulk_i32 s0, 0x1600
	s_add_u32 s4, s34, s0
	s_addc_u32 s5, s35, s5
	s_add_u32 s6, s4, 0x1400
	s_addc_u32 s7, s5, 0
	s_mov_b32 s4, 0xbfb8aa3b
	s_mov_b32 s0, 0x800000
	s_mov_b32 s5, 0x3f317217
	s_mov_b32 s6, 0x7f800000
	s_waitcnt vmcnt(0)
	v_mov_b32_e32 v44, v128
	v_mov_b32_e32 v45, v129
	v_mov_b32_e32 v46, v130
	v_mov_b32_e32 v47, v131
	v_mov_b32_e32 v16, v132
	v_mov_b32_e32 v17, v133
	v_mov_b32_e32 v18, v134
	v_mov_b32_e32 v19, v135
	v_lshlrev_b32_e32 v20, 16, v44
	v_and_b32_e32 v21, 0xffff0000, v44
	v_fma_f32 v48, v112, v20, v113
	v_lshlrev_b32_e32 v43, 16, v45
	v_fma_f32 v49, v118, v20, v122
	v_fmac_f32_e32 v48, v111, v21
	v_and_b32_e32 v44, 0xffff0000, v45
	v_fmac_f32_e32 v49, v117, v21
	v_fmac_f32_e32 v48, v110, v43
	v_lshlrev_b32_e32 v45, 16, v46
	v_fmac_f32_e32 v49, v116, v43
	v_fmac_f32_e32 v48, v109, v44
	v_and_b32_e32 v46, 0xffff0000, v46
	v_fmac_f32_e32 v49, v121, v44
	v_fmac_f32_e32 v48, v115, v45
	v_and_b32_e32 v20, 0xffff0000, v47
	v_lshlrev_b32_e32 v21, 16, v47
	v_fmac_f32_e32 v49, v120, v45
	v_fmac_f32_e32 v48, v114, v46
	v_pk_mul_f32 v[44:45], v[40:41], v[20:21]
	v_pk_mul_f32 v[20:21], v[32:33], v[20:21]
	v_fmac_f32_e32 v49, v119, v46
	v_add_f32_e32 v21, v21, v48
	v_add_f32_e32 v43, v45, v49
	v_add_f32_e32 v46, v20, v21
	v_and_b32_e32 v20, 0xffff0000, v16
	v_lshlrev_b32_e32 v21, 16, v16
	v_add_f32_e32 v43, v44, v43
	v_pk_mul_f32 v[44:45], v[38:39], v[20:21]
	v_pk_mul_f32 v[20:21], v[30:31], v[20:21]
	v_add_f32_e32 v16, v45, v43
	v_add_f32_e32 v21, v21, v46
	v_add_f32_e32 v44, v44, v16
	v_and_b32_e32 v16, 0xffff0000, v17
	v_lshlrev_b32_e32 v17, 16, v17
	v_add_f32_e32 v43, v20, v21
	v_pk_mul_f32 v[20:21], v[36:37], v[16:17]
	v_pk_mul_f32 v[16:17], v[26:27], v[16:17]
	v_add_f32_e32 v21, v21, v44
	v_add_f32_e32 v17, v17, v43
	v_add_f32_e32 v43, v16, v17
	v_and_b32_e32 v16, 0xffff0000, v18
	v_lshlrev_b32_e32 v17, 16, v18
	v_add_f32_e32 v44, v20, v21
	v_pk_mul_f32 v[20:21], v[34:35], v[16:17]
	v_pk_mul_f32 v[16:17], v[24:25], v[16:17]
	v_add_f32_e32 v18, v21, v44
	v_add_f32_e32 v17, v17, v43
	v_add_f32_e32 v21, v16, v17
	v_and_b32_e32 v16, 0xffff0000, v19
	v_lshlrev_b32_e32 v17, 16, v19
	v_add_f32_e32 v20, v20, v18
	v_pk_mul_f32 v[18:19], v[28:29], v[16:17]
	v_pk_mul_f32 v[16:17], v[22:23], v[16:17]
	v_add_f32_e32 v19, v19, v20
	v_add_f32_e32 v17, v17, v21
	v_add_f32_e32 v17, v16, v17
	v_min_f32_e32 v16, 0, v17
	v_mul_f32_e64 v17, |v17|, s4
	v_exp_f32_e32 v17, v17
	v_add_f32_e32 v19, v18, v19
	v_add_f32_e32 v17, 1.0, v17
	v_cmp_gt_f32_e32 vcc, s0, v17
	s_nop 1
	v_cndmask_b32_e64 v18, 0, 32, vcc
	v_ldexp_f32 v17, v17, v18
	v_log_f32_e32 v17, v17
	s_nop 0
	v_mul_f32_e32 v18, 0x3f317217, v17
	v_fma_f32 v18, v17, s5, -v18
	v_fmac_f32_e32 v18, 0x3377d1cf, v17
	v_fmac_f32_e32 v18, 0x3f317217, v17
	v_cmp_lt_f32_e64 s[22:23], |v17|, s6
	s_nop 1
	v_cndmask_b32_e64 v17, v17, v18, s[22:23]
	v_cndmask_b32_e32 v18, 0, v222, vcc
	v_sub_f32_e32 v18, v17, v18
	v_min_f32_e32 v17, 0, v19
	v_mul_f32_e64 v19, |v19|, s4
	v_exp_f32_e32 v19, v19
	s_nop 0
	v_add_f32_e32 v19, 1.0, v19
	v_cmp_gt_f32_e32 vcc, s0, v19
	s_mov_b32 s0, 0x3d800000
	s_nop 0
	v_cndmask_b32_e64 v20, 0, 32, vcc
	v_ldexp_f32 v19, v19, v20
	v_log_f32_e32 v19, v19
	s_nop 0
	v_mul_f32_e32 v20, 0x3f317217, v19
	v_fma_f32 v20, v19, s5, -v20
	v_fmac_f32_e32 v20, 0x3377d1cf, v19
	v_fmac_f32_e32 v20, 0x3f317217, v19
	v_cmp_lt_f32_e64 s[22:23], |v19|, s6
	s_nop 1
	v_cndmask_b32_e64 v19, v19, v20, s[22:23]
	v_cndmask_b32_e32 v20, 0, v222, vcc
	v_sub_f32_e32 v19, v19, v20
	v_pk_add_f32 v[16:17], v[16:17], v[18:19] neg_lo:[0,1] neg_hi:[0,1]
	s_nop 0
	v_pk_fma_f32 v[20:21], v[16:17], s[0:1], 0 op_sel_hi:[1,0,0]
.LBB0_651:
	s_and_b64 vcc, exec, s[20:21]
	v_mov_b32_e32 v43, 0
	s_cbranch_vccnz .LBB0_653
	s_add_i32 s0, s58, s51
	s_mul_hi_i32 s5, s0, 0x1600
	s_mulk_i32 s0, 0x1600
	s_add_u32 s4, s34, s0
	s_addc_u32 s5, s35, s5
	s_add_u32 s6, s4, 0x1400
	s_addc_u32 s7, s5, 0
	s_mov_b32 s4, 0xbfb8aa3b
	s_mov_b32 s0, 0x800000
	s_mov_b32 s5, 0x3f317217
	s_mov_b32 s6, 0x7f800000
	s_waitcnt vmcnt(0)
	v_mov_b32_e32 v42, v136
	v_mov_b32_e32 v43, v137
	v_mov_b32_e32 v44, v138
	v_mov_b32_e32 v45, v139
	v_mov_b32_e32 v16, v140
	v_mov_b32_e32 v17, v141
	v_mov_b32_e32 v18, v142
	v_mov_b32_e32 v19, v143
	v_lshlrev_b32_e32 v46, 16, v42
	v_and_b32_e32 v42, 0xffff0000, v42
	v_fma_f32 v49, v112, v46, v113
	v_fma_f32 v46, v118, v46, v122
	v_lshlrev_b32_e32 v47, 16, v43
	v_fmac_f32_e32 v49, v111, v42
	v_fmac_f32_e32 v46, v117, v42
	v_and_b32_e32 v43, 0xffff0000, v43
	v_fmac_f32_e32 v49, v110, v47
	v_fmac_f32_e32 v46, v116, v47
	v_lshlrev_b32_e32 v48, 16, v44
	v_fmac_f32_e32 v49, v109, v43
	v_fmac_f32_e32 v46, v121, v43
	v_and_b32_e32 v44, 0xffff0000, v44
	v_fmac_f32_e32 v49, v115, v48
	v_fmac_f32_e32 v46, v120, v48
	v_and_b32_e32 v42, 0xffff0000, v45
	v_lshlrev_b32_e32 v43, 16, v45
	v_fmac_f32_e32 v49, v114, v44
	v_fmac_f32_e32 v46, v119, v44
	v_pk_mul_f32 v[44:45], v[32:33], v[42:43]
	v_pk_mul_f32 v[42:43], v[40:41], v[42:43]
	v_add_f32_e32 v45, v45, v49
	v_add_f32_e32 v43, v43, v46
	v_add_f32_e32 v46, v42, v43
	v_and_b32_e32 v42, 0xffff0000, v16
	v_lshlrev_b32_e32 v43, 16, v16
	v_add_f32_e32 v47, v44, v45
	v_pk_mul_f32 v[44:45], v[30:31], v[42:43]
	v_pk_mul_f32 v[42:43], v[38:39], v[42:43]
	v_add_f32_e32 v16, v45, v47
	v_add_f32_e32 v44, v44, v16
	v_add_f32_e32 v16, v43, v46
	v_add_f32_e32 v45, v42, v16
	v_and_b32_e32 v16, 0xffff0000, v17
	v_lshlrev_b32_e32 v17, 16, v17
	v_pk_mul_f32 v[42:43], v[26:27], v[16:17]
; template <bool FINAL>
; DI void gla_unit(KA a, int l, int item, LAS unsigned char* lds) {
;     ...
;         for (int jj = 0; jj < 8; ++jj) {
;             const int t = 8 * tg + jj;
;             float ga = 0.f, gb = 0.f;
;             if (t < nvalid) {
;                 const u32x4* lp = (const u32x4*)(U + (size_t)(row0 + t) * UN + U_LR);
;                 float lr[16]; unpack8(lp[0], lr); unpack8(lp[1], lr + 8);
;                 float za = bg[0], zb = bg[1];
; #pragma unroll
;                 for (int e = 0; e < 16; ++e) { za += wg[0][e] * lr[e]; zb += wg[1][e] * lr[e]; }
;                 ga = (fminf(za, 0.f) - __logf(1.f + __expf(-fabsf(za)))) * (1.f / 16.f);
;                 gb = (fminf(zb, 0.f) - __logf(1.f + __expf(-fabsf(zb)))) * (1.f / 16.f);
;             }
;             run0 += ga; run1 += gb; bl[0][jj] = run0; bl[1][jj] = run1;
;         }
	v_pk_mul_f32 v[16:17], v[36:37], v[16:17]
	v_add_f32_e32 v43, v43, v44
	v_add_f32_e32 v17, v17, v45
	v_add_f32_e32 v45, v16, v17
	v_and_b32_e32 v16, 0xffff0000, v18
	v_lshlrev_b32_e32 v17, 16, v18
	v_add_f32_e32 v44, v42, v43
	v_pk_mul_f32 v[42:43], v[24:25], v[16:17]
	v_pk_mul_f32 v[16:17], v[34:35], v[16:17]
	v_add_f32_e32 v18, v43, v44
	v_add_f32_e32 v17, v17, v45
	v_add_f32_e32 v43, v16, v17
	v_and_b32_e32 v16, 0xffff0000, v19
	v_lshlrev_b32_e32 v17, 16, v19
	v_add_f32_e32 v42, v42, v18
	v_pk_mul_f32 v[18:19], v[22:23], v[16:17]
	v_pk_mul_f32 v[16:17], v[28:29], v[16:17]
	v_add_f32_e32 v19, v19, v42
	v_add_f32_e32 v18, v18, v19
	v_add_f32_e32 v17, v17, v43
	v_add_f32_e32 v42, v16, v17
	v_mul_f32_e64 v16, |v18|, s4
	v_exp_f32_e32 v16, v16
	v_min_f32_e32 v17, 0, v18
	v_add_f32_e32 v16, 1.0, v16
	v_cmp_gt_f32_e32 vcc, s0, v16
	s_nop 1
	v_cndmask_b32_e64 v18, 0, 32, vcc
	v_ldexp_f32 v16, v16, v18
	v_log_f32_e32 v16, v16
	s_nop 0
	v_mul_f32_e32 v18, 0x3f317217, v16
	v_fma_f32 v18, v16, s5, -v18
	v_fmac_f32_e32 v18, 0x3377d1cf, v16
	v_fmac_f32_e32 v18, 0x3f317217, v16
	v_cmp_lt_f32_e64 s[20:21], |v16|, s6
	s_nop 1
	v_cndmask_b32_e64 v16, v16, v18, s[20:21]
	v_cndmask_b32_e32 v18, 0, v222, vcc
	v_sub_f32_e32 v19, v16, v18
	v_mul_f32_e64 v18, |v42|, s4
	v_exp_f32_e32 v18, v18
	v_min_f32_e32 v16, 0, v42
	v_add_f32_e32 v18, 1.0, v18
	v_cmp_gt_f32_e32 vcc, s0, v18
	s_mov_b32 s0, 0x3d800000
	s_nop 0
	v_cndmask_b32_e64 v42, 0, 32, vcc
	v_ldexp_f32 v18, v18, v42
	v_log_f32_e32 v18, v18
	s_nop 0
	v_mul_f32_e32 v42, 0x3f317217, v18
	v_fma_f32 v42, v18, s5, -v42
	v_fmac_f32_e32 v42, 0x3377d1cf, v18
	v_fmac_f32_e32 v42, 0x3f317217, v18
	v_cmp_lt_f32_e64 s[20:21], |v18|, s6
	s_nop 1
	v_cndmask_b32_e64 v18, v18, v42, s[20:21]
	v_cndmask_b32_e32 v42, 0, v222, vcc
	v_sub_f32_e32 v18, v18, v42
	v_pk_add_f32 v[16:17], v[16:17], v[18:19] neg_lo:[0,1] neg_hi:[0,1]
	s_nop 0
	v_pk_mul_f32 v[42:43], v[16:17], s[0:1] op_sel_hi:[1,0]
.LBB0_653:
	v_mov_b32_e32 v44, 0
	s_and_b64 vcc, exec, s[18:19]
	v_mov_b32_e32 v46, 0
	v_mov_b32_e32 v47, 0
	s_cbranch_vccnz .LBB0_655
	s_add_i32 s0, s57, s51
	s_mul_hi_i32 s5, s0, 0x1600
	s_mulk_i32 s0, 0x1600
	s_add_u32 s4, s34, s0
	s_addc_u32 s5, s35, s5
	s_add_u32 s6, s4, 0x1400
	s_addc_u32 s7, s5, 0
	s_mov_b32 s4, 0xbfb8aa3b
	s_mov_b32 s0, 0x800000
	s_mov_b32 s5, 0x3f317217
	s_mov_b32 s6, 0x7f800000
	s_waitcnt vmcnt(0)
	v_mov_b32_e32 v46, v154
	v_mov_b32_e32 v47, v155
	v_mov_b32_e32 v48, v156
	v_mov_b32_e32 v49, v157
	v_mov_b32_e32 v16, v158
	v_mov_b32_e32 v17, v159
	v_mov_b32_e32 v18, v160
	v_mov_b32_e32 v19, v161
	v_lshlrev_b32_e32 v45, 16, v46
	v_and_b32_e32 v46, 0xffff0000, v46
	v_fma_f32 v52, v112, v45, v113
	v_fma_f32 v45, v118, v45, v122
	v_lshlrev_b32_e32 v50, 16, v47
	v_fmac_f32_e32 v52, v111, v46
	v_fmac_f32_e32 v45, v117, v46
	v_and_b32_e32 v47, 0xffff0000, v47
	v_fmac_f32_e32 v52, v110, v50
	v_fmac_f32_e32 v45, v116, v50
	v_lshlrev_b32_e32 v51, 16, v48
	v_fmac_f32_e32 v52, v109, v47
	v_fmac_f32_e32 v45, v121, v47
	v_and_b32_e32 v48, 0xffff0000, v48
	v_fmac_f32_e32 v52, v115, v51
	v_fmac_f32_e32 v45, v120, v51
	v_and_b32_e32 v46, 0xffff0000, v49
	v_lshlrev_b32_e32 v47, 16, v49
	v_fmac_f32_e32 v52, v114, v48
	v_fmac_f32_e32 v45, v119, v48
	v_pk_mul_f32 v[48:49], v[32:33], v[46:47]
	v_pk_mul_f32 v[46:47], v[40:41], v[46:47]
	v_add_f32_e32 v49, v49, v52
	v_add_f32_e32 v45, v47, v45
	v_add_f32_e32 v45, v46, v45
	v_and_b32_e32 v46, 0xffff0000, v16
	v_lshlrev_b32_e32 v47, 16, v16
	v_add_f32_e32 v50, v48, v49
	v_pk_mul_f32 v[48:49], v[30:31], v[46:47]
	v_pk_mul_f32 v[46:47], v[38:39], v[46:47]
	v_add_f32_e32 v16, v49, v50
	v_add_f32_e32 v48, v48, v16
	v_add_f32_e32 v16, v47, v45
	v_add_f32_e32 v45, v46, v16
	v_and_b32_e32 v16, 0xffff0000, v17
	v_lshlrev_b32_e32 v17, 16, v17
	v_pk_mul_f32 v[46:47], v[26:27], v[16:17]
	v_pk_mul_f32 v[16:17], v[36:37], v[16:17]
	v_add_f32_e32 v47, v47, v48
	v_add_f32_e32 v17, v17, v45
	v_add_f32_e32 v45, v16, v17
	v_and_b32_e32 v16, 0xffff0000, v18
	v_lshlrev_b32_e32 v17, 16, v18
	v_add_f32_e32 v48, v46, v47
	v_pk_mul_f32 v[46:47], v[24:25], v[16:17]
	v_pk_mul_f32 v[16:17], v[34:35], v[16:17]
	v_add_f32_e32 v18, v47, v48
	v_add_f32_e32 v17, v17, v45
	v_add_f32_e32 v45, v16, v17
	v_and_b32_e32 v16, 0xffff0000, v19
	v_lshlrev_b32_e32 v17, 16, v19
	v_add_f32_e32 v46, v46, v18
	v_pk_mul_f32 v[18:19], v[22:23], v[16:17]
	v_pk_mul_f32 v[16:17], v[28:29], v[16:17]
	v_add_f32_e32 v19, v19, v46
	v_add_f32_e32 v18, v18, v19
	v_add_f32_e32 v17, v17, v45
	v_add_f32_e32 v45, v16, v17
	v_mul_f32_e64 v16, |v18|, s4
	v_exp_f32_e32 v16, v16
	v_min_f32_e32 v17, 0, v18
	v_add_f32_e32 v16, 1.0, v16
	v_cmp_gt_f32_e32 vcc, s0, v16
	s_nop 1
	v_cndmask_b32_e64 v18, 0, 32, vcc
	v_ldexp_f32 v16, v16, v18
	v_log_f32_e32 v16, v16
	s_nop 0
	v_mul_f32_e32 v18, 0x3f317217, v16
	v_fma_f32 v18, v16, s5, -v18
	v_fmac_f32_e32 v18, 0x3377d1cf, v16
	v_fmac_f32_e32 v18, 0x3f317217, v16
	v_cmp_lt_f32_e64 s[18:19], |v16|, s6
	s_nop 1
	v_cndmask_b32_e64 v16, v16, v18, s[18:19]
	v_cndmask_b32_e32 v18, 0, v222, vcc
	v_sub_f32_e32 v19, v16, v18
	v_mul_f32_e64 v18, |v45|, s4
	v_exp_f32_e32 v18, v18
	v_min_f32_e32 v16, 0, v45
	v_add_f32_e32 v18, 1.0, v18
	v_cmp_gt_f32_e32 vcc, s0, v18
	s_mov_b32 s0, 0x3d800000
	s_nop 0
	v_cndmask_b32_e64 v45, 0, 32, vcc
	v_ldexp_f32 v18, v18, v45
	v_log_f32_e32 v18, v18
	s_nop 0
	v_mul_f32_e32 v45, 0x3f317217, v18
	v_fma_f32 v45, v18, s5, -v45
	v_fmac_f32_e32 v45, 0x3377d1cf, v18
	v_fmac_f32_e32 v45, 0x3f317217, v18
	v_cmp_lt_f32_e64 s[18:19], |v18|, s6
	s_nop 1
	v_cndmask_b32_e64 v18, v18, v45, s[18:19]
	v_cndmask_b32_e32 v45, 0, v222, vcc
	v_sub_f32_e32 v18, v18, v45
	v_pk_add_f32 v[16:17], v[16:17], v[18:19] neg_lo:[0,1] neg_hi:[0,1]
	s_nop 0
	v_pk_mul_f32 v[46:47], v[16:17], s[0:1] op_sel_hi:[1,0]
; template <bool FINAL>
; DI void gla_unit(KA a, int l, int item, LAS unsigned char* lds) {
;     ...
;         for (int jj = 0; jj < 8; ++jj) {
;             const int t = 8 * tg + jj;
;             float ga = 0.f, gb = 0.f;
;             if (t < nvalid) {
;                 const u32x4* lp = (const u32x4*)(U + (size_t)(row0 + t) * UN + U_LR);
;                 float lr[16]; unpack8(lp[0], lr); unpack8(lp[1], lr + 8);
;                 float za = bg[0], zb = bg[1];
; #pragma unroll
;                 for (int e = 0; e < 16; ++e) { za += wg[0][e] * lr[e]; zb += wg[1][e] * lr[e]; }
;                 ga = (fminf(za, 0.f) - __logf(1.f + __expf(-fabsf(za)))) * (1.f / 16.f);
;                 gb = (fminf(zb, 0.f) - __logf(1.f + __expf(-fabsf(zb)))) * (1.f / 16.f);
;             }
;             run0 += ga; run1 += gb; bl[0][jj] = run0; bl[1][jj] = run1;
;         }
.LBB0_655:
	s_and_b64 vcc, exec, s[16:17]
	v_mov_b32_e32 v45, 0
	s_cbranch_vccnz .LBB0_657
	s_add_i32 s0, s56, s51
	s_mul_hi_i32 s5, s0, 0x1600
	s_mulk_i32 s0, 0x1600
	s_add_u32 s4, s34, s0
	s_addc_u32 s5, s35, s5
	s_add_u32 s6, s4, 0x1400
	s_addc_u32 s7, s5, 0
	s_mov_b32 s4, 0xbfb8aa3b
	s_mov_b32 s0, 0x800000
	s_mov_b32 s5, 0x3f317217
	s_mov_b32 s6, 0x7f800000
	s_waitcnt vmcnt(0)
	v_mov_b32_e32 v48, v162
	v_mov_b32_e32 v49, v163
	v_mov_b32_e32 v50, v164
	v_mov_b32_e32 v51, v165
	v_mov_b32_e32 v16, v166
	v_mov_b32_e32 v17, v167
	v_mov_b32_e32 v18, v168
	v_mov_b32_e32 v19, v169
	v_lshlrev_b32_e32 v44, 16, v48
	v_and_b32_e32 v45, 0xffff0000, v48
	v_fma_f32 v54, v118, v44, v122
	v_lshlrev_b32_e32 v48, 16, v49
	v_fma_f32 v53, v112, v44, v113
	v_fmac_f32_e32 v54, v117, v45
	v_and_b32_e32 v49, 0xffff0000, v49
	v_fmac_f32_e32 v53, v111, v45
	v_fmac_f32_e32 v54, v116, v48
	v_lshlrev_b32_e32 v52, 16, v50
	v_fmac_f32_e32 v53, v110, v48
	v_fmac_f32_e32 v54, v121, v49
	v_and_b32_e32 v50, 0xffff0000, v50
	v_fmac_f32_e32 v53, v109, v49
	v_fmac_f32_e32 v54, v120, v52
	v_and_b32_e32 v44, 0xffff0000, v51
	v_lshlrev_b32_e32 v45, 16, v51
	v_fmac_f32_e32 v53, v115, v52
	v_fmac_f32_e32 v54, v119, v50
	v_pk_mul_f32 v[48:49], v[32:33], v[44:45]
	v_pk_mul_f32 v[44:45], v[40:41], v[44:45]
	v_fmac_f32_e32 v53, v114, v50
	v_add_f32_e32 v45, v45, v54
	v_add_f32_e32 v49, v49, v53
	v_add_f32_e32 v51, v44, v45
	v_and_b32_e32 v44, 0xffff0000, v16
	v_lshlrev_b32_e32 v45, 16, v16
	v_add_f32_e32 v50, v48, v49
	v_pk_mul_f32 v[48:49], v[30:31], v[44:45]
	v_pk_mul_f32 v[44:45], v[38:39], v[44:45]
	v_add_f32_e32 v16, v49, v50
	v_add_f32_e32 v48, v48, v16
	v_add_f32_e32 v16, v45, v51
	v_add_f32_e32 v49, v44, v16
	v_and_b32_e32 v16, 0xffff0000, v17
	v_lshlrev_b32_e32 v17, 16, v17
	v_pk_mul_f32 v[44:45], v[26:27], v[16:17]
	v_pk_mul_f32 v[16:17], v[36:37], v[16:17]
	v_add_f32_e32 v45, v45, v48
	v_add_f32_e32 v17, v17, v49
	v_add_f32_e32 v49, v16, v17
	v_and_b32_e32 v16, 0xffff0000, v18
	v_lshlrev_b32_e32 v17, 16, v18
	v_add_f32_e32 v48, v44, v45
	v_pk_mul_f32 v[44:45], v[24:25], v[16:17]
	v_pk_mul_f32 v[16:17], v[34:35], v[16:17]
	v_add_f32_e32 v18, v45, v48
	v_add_f32_e32 v17, v17, v49
	v_add_f32_e32 v45, v16, v17
	v_and_b32_e32 v16, 0xffff0000, v19
	v_lshlrev_b32_e32 v17, 16, v19
	v_add_f32_e32 v44, v44, v18
	v_pk_mul_f32 v[18:19], v[22:23], v[16:17]
	v_pk_mul_f32 v[16:17], v[28:29], v[16:17]
	v_add_f32_e32 v19, v19, v44
	v_add_f32_e32 v18, v18, v19
	v_add_f32_e32 v17, v17, v45
	v_add_f32_e32 v44, v16, v17
	v_mul_f32_e64 v16, |v18|, s4
	v_exp_f32_e32 v16, v16
	v_min_f32_e32 v17, 0, v18
	v_add_f32_e32 v16, 1.0, v16
	v_cmp_gt_f32_e32 vcc, s0, v16
	s_nop 1
	v_cndmask_b32_e64 v18, 0, 32, vcc
	v_ldexp_f32 v16, v16, v18
	v_log_f32_e32 v16, v16
	s_nop 0
	v_mul_f32_e32 v18, 0x3f317217, v16
	v_fma_f32 v18, v16, s5, -v18
	v_fmac_f32_e32 v18, 0x3377d1cf, v16
	v_fmac_f32_e32 v18, 0x3f317217, v16
	v_cmp_lt_f32_e64 s[16:17], |v16|, s6
	s_nop 1
	v_cndmask_b32_e64 v16, v16, v18, s[16:17]
	v_cndmask_b32_e32 v18, 0, v222, vcc
	v_sub_f32_e32 v19, v16, v18
	v_mul_f32_e64 v18, |v44|, s4
	v_exp_f32_e32 v18, v18
	v_min_f32_e32 v16, 0, v44
	v_add_f32_e32 v18, 1.0, v18
	v_cmp_gt_f32_e32 vcc, s0, v18
	s_mov_b32 s0, 0x3d800000
	s_nop 0
	v_cndmask_b32_e64 v44, 0, 32, vcc
	v_ldexp_f32 v18, v18, v44
	v_log_f32_e32 v18, v18
	s_nop 0
	v_mul_f32_e32 v44, 0x3f317217, v18
	v_fma_f32 v44, v18, s5, -v44
	v_fmac_f32_e32 v44, 0x3377d1cf, v18
	v_fmac_f32_e32 v44, 0x3f317217, v18
	v_cmp_lt_f32_e64 s[16:17], |v18|, s6
	s_nop 1
	v_cndmask_b32_e64 v18, v18, v44, s[16:17]
	v_cndmask_b32_e32 v44, 0, v222, vcc
	v_sub_f32_e32 v18, v18, v44
	v_pk_add_f32 v[16:17], v[16:17], v[18:19] neg_lo:[0,1] neg_hi:[0,1]
	s_nop 0
	v_pk_mul_f32 v[44:45], v[16:17], s[0:1] op_sel_hi:[1,0]
.LBB0_657:
	v_mov_b32_e32 v48, 0
	s_and_b64 vcc, exec, s[14:15]
	v_mov_b32_e32 v50, 0
	v_mov_b32_e32 v51, 0
	s_cbranch_vccnz .LBB0_659
	s_add_i32 s0, s55, s51
	s_mul_hi_i32 s5, s0, 0x1600
	s_mulk_i32 s0, 0x1600
	s_add_u32 s4, s34, s0
	s_addc_u32 s5, s35, s5
	s_add_u32 s6, s4, 0x1400
	s_addc_u32 s7, s5, 0
	s_mov_b32 s4, 0xbfb8aa3b
	s_mov_b32 s0, 0x800000
	s_mov_b32 s5, 0x3f317217
	s_mov_b32 s6, 0x7f800000
	s_waitcnt vmcnt(0)
	v_mov_b32_e32 v50, v172
	v_mov_b32_e32 v51, v173
	v_mov_b32_e32 v52, v174
	v_mov_b32_e32 v53, v175
	v_mov_b32_e32 v16, v176
	v_mov_b32_e32 v17, v177
	v_mov_b32_e32 v18, v178
	v_mov_b32_e32 v19, v179
	v_lshlrev_b32_e32 v49, 16, v50
	v_and_b32_e32 v50, 0xffff0000, v50
	v_fma_f32 v123, v112, v49, v113
	v_fma_f32 v49, v118, v49, v122
	v_lshlrev_b32_e32 v54, 16, v51
	v_fmac_f32_e32 v123, v111, v50
	v_fmac_f32_e32 v49, v117, v50
	v_and_b32_e32 v51, 0xffff0000, v51
	v_fmac_f32_e32 v123, v110, v54
	v_fmac_f32_e32 v49, v116, v54
	v_lshlrev_b32_e32 v55, 16, v52
	v_fmac_f32_e32 v123, v109, v51
	v_fmac_f32_e32 v49, v121, v51
	v_and_b32_e32 v52, 0xffff0000, v52
	v_fmac_f32_e32 v123, v115, v55
	v_fmac_f32_e32 v49, v120, v55
	v_and_b32_e32 v50, 0xffff0000, v53
	v_lshlrev_b32_e32 v51, 16, v53
	v_fmac_f32_e32 v123, v114, v52
	v_fmac_f32_e32 v49, v119, v52
	v_pk_mul_f32 v[52:53], v[32:33], v[50:51]
	v_pk_mul_f32 v[50:51], v[40:41], v[50:51]
	v_add_f32_e32 v53, v53, v123
	v_add_f32_e32 v49, v51, v49
	v_add_f32_e32 v49, v50, v49
	v_and_b32_e32 v50, 0xffff0000, v16
	v_lshlrev_b32_e32 v51, 16, v16
	v_add_f32_e32 v54, v52, v53
	v_pk_mul_f32 v[52:53], v[30:31], v[50:51]
	v_pk_mul_f32 v[50:51], v[38:39], v[50:51]
	v_add_f32_e32 v16, v53, v54
	v_add_f32_e32 v52, v52, v16
	v_add_f32_e32 v16, v51, v49
	v_add_f32_e32 v49, v50, v16
	v_and_b32_e32 v16, 0xffff0000, v17
	v_lshlrev_b32_e32 v17, 16, v17
	v_pk_mul_f32 v[50:51], v[26:27], v[16:17]
; template <bool FINAL>
; DI void gla_unit(KA a, int l, int item, LAS unsigned char* lds) {
;     ...
;         for (int jj = 0; jj < 8; ++jj) {
;             const int t = 8 * tg + jj;
;             float ga = 0.f, gb = 0.f;
;             if (t < nvalid) {
;                 const u32x4* lp = (const u32x4*)(U + (size_t)(row0 + t) * UN + U_LR);
;                 float lr[16]; unpack8(lp[0], lr); unpack8(lp[1], lr + 8);
;                 float za = bg[0], zb = bg[1];
; #pragma unroll
;                 for (int e = 0; e < 16; ++e) { za += wg[0][e] * lr[e]; zb += wg[1][e] * lr[e]; }
;                 ga = (fminf(za, 0.f) - __logf(1.f + __expf(-fabsf(za)))) * (1.f / 16.f);
;                 gb = (fminf(zb, 0.f) - __logf(1.f + __expf(-fabsf(zb)))) * (1.f / 16.f);
;             }
;             run0 += ga; run1 += gb; bl[0][jj] = run0; bl[1][jj] = run1;
;         }
	v_pk_mul_f32 v[16:17], v[36:37], v[16:17]
	v_add_f32_e32 v51, v51, v52
	v_add_f32_e32 v17, v17, v49
	v_add_f32_e32 v49, v16, v17
	v_and_b32_e32 v16, 0xffff0000, v18
	v_lshlrev_b32_e32 v17, 16, v18
	v_add_f32_e32 v52, v50, v51
	v_pk_mul_f32 v[50:51], v[24:25], v[16:17]
	v_pk_mul_f32 v[16:17], v[34:35], v[16:17]
	v_add_f32_e32 v18, v51, v52
	v_add_f32_e32 v17, v17, v49
	v_add_f32_e32 v49, v16, v17
	v_and_b32_e32 v16, 0xffff0000, v19
	v_lshlrev_b32_e32 v17, 16, v19
	v_add_f32_e32 v50, v50, v18
	v_pk_mul_f32 v[18:19], v[22:23], v[16:17]
	v_pk_mul_f32 v[16:17], v[28:29], v[16:17]
	v_add_f32_e32 v19, v19, v50
	v_add_f32_e32 v18, v18, v19
	v_add_f32_e32 v17, v17, v49
	v_add_f32_e32 v49, v16, v17
	v_mul_f32_e64 v16, |v18|, s4
	v_exp_f32_e32 v16, v16
	v_min_f32_e32 v17, 0, v18
	v_add_f32_e32 v16, 1.0, v16
	v_cmp_gt_f32_e32 vcc, s0, v16
	s_nop 1
	v_cndmask_b32_e64 v18, 0, 32, vcc
	v_ldexp_f32 v16, v16, v18
	v_log_f32_e32 v16, v16
	s_nop 0
	v_mul_f32_e32 v18, 0x3f317217, v16
	v_fma_f32 v18, v16, s5, -v18
	v_fmac_f32_e32 v18, 0x3377d1cf, v16
	v_fmac_f32_e32 v18, 0x3f317217, v16
	v_cmp_lt_f32_e64 s[14:15], |v16|, s6
	s_nop 1
	v_cndmask_b32_e64 v16, v16, v18, s[14:15]
	v_cndmask_b32_e32 v18, 0, v222, vcc
	v_sub_f32_e32 v19, v16, v18
	v_mul_f32_e64 v18, |v49|, s4
	v_exp_f32_e32 v18, v18
	v_min_f32_e32 v16, 0, v49
	v_add_f32_e32 v18, 1.0, v18
	v_cmp_gt_f32_e32 vcc, s0, v18
	s_mov_b32 s0, 0x3d800000
	s_nop 0
	v_cndmask_b32_e64 v49, 0, 32, vcc
	v_ldexp_f32 v18, v18, v49
	v_log_f32_e32 v18, v18
	s_nop 0
	v_mul_f32_e32 v49, 0x3f317217, v18
	v_fma_f32 v49, v18, s5, -v49
	v_fmac_f32_e32 v49, 0x3377d1cf, v18
	v_fmac_f32_e32 v49, 0x3f317217, v18
	v_cmp_lt_f32_e64 s[14:15], |v18|, s6
	s_nop 1
	v_cndmask_b32_e64 v18, v18, v49, s[14:15]
	v_cndmask_b32_e32 v49, 0, v222, vcc
	v_sub_f32_e32 v18, v18, v49
	v_pk_add_f32 v[16:17], v[16:17], v[18:19] neg_lo:[0,1] neg_hi:[0,1]
	s_nop 0
	v_pk_mul_f32 v[50:51], v[16:17], s[0:1] op_sel_hi:[1,0]
.LBB0_659:
	s_and_b64 vcc, exec, s[12:13]
	v_mov_b32_e32 v49, 0
	s_cbranch_vccnz .LBB0_661
	s_add_i32 s0, s54, s51
	s_mul_hi_i32 s5, s0, 0x1600
	s_mulk_i32 s0, 0x1600
	s_add_u32 s4, s34, s0
	s_addc_u32 s5, s35, s5
	s_add_u32 s6, s4, 0x1400
	s_addc_u32 s7, s5, 0
	s_mov_b32 s4, 0xbfb8aa3b
	s_mov_b32 s0, 0x800000
	s_mov_b32 s5, 0x3f317217
	s_mov_b32 s6, 0x7f800000
	s_waitcnt vmcnt(0)
	v_mov_b32_e32 v52, v180
	v_mov_b32_e32 v53, v181
	v_mov_b32_e32 v54, v182
	v_mov_b32_e32 v55, v183
	v_mov_b32_e32 v16, v184
	v_mov_b32_e32 v17, v185
	v_mov_b32_e32 v18, v186
	v_mov_b32_e32 v19, v187
	v_lshlrev_b32_e32 v48, 16, v52
	v_and_b32_e32 v49, 0xffff0000, v52
	v_fma_f32 v125, v118, v48, v122
	v_lshlrev_b32_e32 v52, 16, v53
	v_fma_f32 v124, v112, v48, v113
	v_fmac_f32_e32 v125, v117, v49
	v_and_b32_e32 v53, 0xffff0000, v53
	v_fmac_f32_e32 v124, v111, v49
	v_fmac_f32_e32 v125, v116, v52
	v_lshlrev_b32_e32 v123, 16, v54
	v_fmac_f32_e32 v124, v110, v52
	v_fmac_f32_e32 v125, v121, v53
	v_and_b32_e32 v54, 0xffff0000, v54
	v_fmac_f32_e32 v124, v109, v53
	v_fmac_f32_e32 v125, v120, v123
	v_and_b32_e32 v48, 0xffff0000, v55
	v_lshlrev_b32_e32 v49, 16, v55
	v_fmac_f32_e32 v124, v115, v123
	v_fmac_f32_e32 v125, v119, v54
	v_pk_mul_f32 v[52:53], v[32:33], v[48:49]
	v_pk_mul_f32 v[48:49], v[40:41], v[48:49]
	v_fmac_f32_e32 v124, v114, v54
	v_add_f32_e32 v49, v49, v125
	v_add_f32_e32 v53, v53, v124
	v_add_f32_e32 v55, v48, v49
	v_and_b32_e32 v48, 0xffff0000, v16
	v_lshlrev_b32_e32 v49, 16, v16
	v_add_f32_e32 v54, v52, v53
	v_pk_mul_f32 v[52:53], v[30:31], v[48:49]
	v_pk_mul_f32 v[48:49], v[38:39], v[48:49]
	v_add_f32_e32 v16, v53, v54
	v_add_f32_e32 v52, v52, v16
	v_add_f32_e32 v16, v49, v55
	v_add_f32_e32 v53, v48, v16
	v_and_b32_e32 v16, 0xffff0000, v17
	v_lshlrev_b32_e32 v17, 16, v17
	v_pk_mul_f32 v[48:49], v[26:27], v[16:17]
	v_pk_mul_f32 v[16:17], v[36:37], v[16:17]
	v_add_f32_e32 v49, v49, v52
	v_add_f32_e32 v17, v17, v53
	v_add_f32_e32 v53, v16, v17
	v_and_b32_e32 v16, 0xffff0000, v18
	v_lshlrev_b32_e32 v17, 16, v18
	v_add_f32_e32 v52, v48, v49
	v_pk_mul_f32 v[48:49], v[24:25], v[16:17]
	v_pk_mul_f32 v[16:17], v[34:35], v[16:17]
	v_add_f32_e32 v18, v49, v52
	v_add_f32_e32 v17, v17, v53
	v_add_f32_e32 v49, v16, v17
	v_and_b32_e32 v16, 0xffff0000, v19
	v_lshlrev_b32_e32 v17, 16, v19
	v_add_f32_e32 v48, v48, v18
	v_pk_mul_f32 v[18:19], v[22:23], v[16:17]
	v_pk_mul_f32 v[16:17], v[28:29], v[16:17]
	v_add_f32_e32 v19, v19, v48
	v_add_f32_e32 v18, v18, v19
	v_add_f32_e32 v17, v17, v49
	v_add_f32_e32 v48, v16, v17
	v_mul_f32_e64 v16, |v18|, s4
	v_exp_f32_e32 v16, v16
	v_min_f32_e32 v17, 0, v18
	v_add_f32_e32 v16, 1.0, v16
	v_cmp_gt_f32_e32 vcc, s0, v16
	s_nop 1
	v_cndmask_b32_e64 v18, 0, 32, vcc
	v_ldexp_f32 v16, v16, v18
	v_log_f32_e32 v16, v16
	s_nop 0
	v_mul_f32_e32 v18, 0x3f317217, v16
	v_fma_f32 v18, v16, s5, -v18
	v_fmac_f32_e32 v18, 0x3377d1cf, v16
	v_fmac_f32_e32 v18, 0x3f317217, v16
	v_cmp_lt_f32_e64 s[12:13], |v16|, s6
	s_nop 1
	v_cndmask_b32_e64 v16, v16, v18, s[12:13]
	v_cndmask_b32_e32 v18, 0, v222, vcc
	v_sub_f32_e32 v19, v16, v18
	v_mul_f32_e64 v18, |v48|, s4
	v_exp_f32_e32 v18, v18
	v_min_f32_e32 v16, 0, v48
	v_add_f32_e32 v18, 1.0, v18
	v_cmp_gt_f32_e32 vcc, s0, v18
	s_mov_b32 s0, 0x3d800000
	s_nop 0
	v_cndmask_b32_e64 v48, 0, 32, vcc
	v_ldexp_f32 v18, v18, v48
	v_log_f32_e32 v18, v18
	s_nop 0
	v_mul_f32_e32 v48, 0x3f317217, v18
	v_fma_f32 v48, v18, s5, -v48
	v_fmac_f32_e32 v48, 0x3377d1cf, v18
	v_fmac_f32_e32 v48, 0x3f317217, v18
	v_cmp_lt_f32_e64 s[12:13], |v18|, s6
	s_nop 1
	v_cndmask_b32_e64 v18, v18, v48, s[12:13]
	v_cndmask_b32_e32 v48, 0, v222, vcc
	v_sub_f32_e32 v18, v18, v48
	v_pk_add_f32 v[16:17], v[16:17], v[18:19] neg_lo:[0,1] neg_hi:[0,1]
	s_nop 0
	v_pk_mul_f32 v[48:49], v[16:17], s[0:1] op_sel_hi:[1,0]
; template <bool FINAL>
; DI void gla_unit(KA a, int l, int item, LAS unsigned char* lds) {
;     ...
;         for (int jj = 0; jj < 8; ++jj) {
;             const int t = 8 * tg + jj;
;             float ga = 0.f, gb = 0.f;
;             if (t < nvalid) {
;                 const u32x4* lp = (const u32x4*)(U + (size_t)(row0 + t) * UN + U_LR);
;                 float lr[16]; unpack8(lp[0], lr); unpack8(lp[1], lr + 8);
;                 float za = bg[0], zb = bg[1];
; #pragma unroll
;                 for (int e = 0; e < 16; ++e) { za += wg[0][e] * lr[e]; zb += wg[1][e] * lr[e]; }
;                 ga = (fminf(za, 0.f) - __logf(1.f + __expf(-fabsf(za)))) * (1.f / 16.f);
;                 gb = (fminf(zb, 0.f) - __logf(1.f + __expf(-fabsf(zb)))) * (1.f / 16.f);
;             }
;             run0 += ga; run1 += gb; bl[0][jj] = run0; bl[1][jj] = run1;
;         }
.LBB0_661:
	v_mov_b32_e32 v52, 0
	s_and_b64 vcc, exec, s[10:11]
	v_mov_b32_e32 v54, 0
	v_mov_b32_e32 v55, 0
	s_cbranch_vccnz .LBB0_663
	s_add_i32 s0, s53, s51
	s_mul_hi_i32 s5, s0, 0x1600
	s_mulk_i32 s0, 0x1600
	s_add_u32 s4, s34, s0
	s_addc_u32 s5, s35, s5
	s_add_u32 s6, s4, 0x1400
	s_addc_u32 s7, s5, 0
	s_mov_b32 s4, 0xbfb8aa3b
	s_mov_b32 s0, 0x800000
	s_mov_b32 s5, 0x3f317217
	s_mov_b32 s6, 0x7f800000
	s_waitcnt vmcnt(0)
	v_mov_b32_e32 v124, v188
	v_mov_b32_e32 v125, v189
	v_mov_b32_e32 v126, v190
	v_mov_b32_e32 v127, v191
	v_mov_b32_e32 v16, v192
	v_mov_b32_e32 v17, v193
	v_mov_b32_e32 v18, v194
	v_mov_b32_e32 v19, v195
	v_lshlrev_b32_e32 v53, 16, v124
	v_and_b32_e32 v54, 0xffff0000, v124
	v_lshlrev_b32_e32 v55, 16, v125
	v_and_b32_e32 v123, 0xffff0000, v125
	v_lshlrev_b32_e32 v124, 16, v126
	v_and_b32_e32 v125, 0xffff0000, v126
	v_fma_f32 v126, v112, v53, v113
	v_fma_f32 v53, v118, v53, v122
	v_fmac_f32_e32 v126, v111, v54
	v_fmac_f32_e32 v53, v117, v54
	v_fmac_f32_e32 v126, v110, v55
	v_fmac_f32_e32 v53, v116, v55
	v_fmac_f32_e32 v126, v109, v123
	v_fmac_f32_e32 v53, v121, v123
	v_fmac_f32_e32 v126, v115, v124
	v_fmac_f32_e32 v53, v120, v124
	v_and_b32_e32 v54, 0xffff0000, v127
	v_lshlrev_b32_e32 v55, 16, v127
	v_fmac_f32_e32 v126, v114, v125
	v_fmac_f32_e32 v53, v119, v125
	v_pk_mul_f32 v[124:125], v[32:33], v[54:55]
	v_pk_mul_f32 v[54:55], v[40:41], v[54:55]
	v_add_f32_e32 v123, v125, v126
	v_add_f32_e32 v53, v55, v53
	v_add_f32_e32 v53, v54, v53
	v_and_b32_e32 v54, 0xffff0000, v16
	v_lshlrev_b32_e32 v55, 16, v16
	v_add_f32_e32 v123, v124, v123
	v_pk_mul_f32 v[124:125], v[30:31], v[54:55]
	v_pk_mul_f32 v[54:55], v[38:39], v[54:55]
	v_add_f32_e32 v16, v125, v123
	v_add_f32_e32 v123, v124, v16
	v_add_f32_e32 v16, v55, v53
	v_add_f32_e32 v53, v54, v16
	v_and_b32_e32 v16, 0xffff0000, v17
	v_lshlrev_b32_e32 v17, 16, v17
	v_pk_mul_f32 v[54:55], v[26:27], v[16:17]
	v_pk_mul_f32 v[16:17], v[36:37], v[16:17]
	v_add_f32_e32 v55, v55, v123
	v_add_f32_e32 v17, v17, v53
	v_add_f32_e32 v53, v16, v17
	v_and_b32_e32 v16, 0xffff0000, v18
	v_lshlrev_b32_e32 v17, 16, v18
	v_add_f32_e32 v123, v54, v55
	v_pk_mul_f32 v[54:55], v[24:25], v[16:17]
	v_pk_mul_f32 v[16:17], v[34:35], v[16:17]
	v_add_f32_e32 v18, v55, v123
	v_add_f32_e32 v17, v17, v53
	v_add_f32_e32 v53, v16, v17
	v_and_b32_e32 v16, 0xffff0000, v19
	v_lshlrev_b32_e32 v17, 16, v19
	v_add_f32_e32 v54, v54, v18
	v_pk_mul_f32 v[18:19], v[22:23], v[16:17]
	v_pk_mul_f32 v[16:17], v[28:29], v[16:17]
	v_add_f32_e32 v19, v19, v54
	v_add_f32_e32 v18, v18, v19
	v_add_f32_e32 v17, v17, v53
	v_add_f32_e32 v53, v16, v17
	v_mul_f32_e64 v16, |v18|, s4
	v_exp_f32_e32 v16, v16
	v_min_f32_e32 v17, 0, v18
	v_add_f32_e32 v16, 1.0, v16
	v_cmp_gt_f32_e32 vcc, s0, v16
	s_nop 1
	v_cndmask_b32_e64 v18, 0, 32, vcc
	v_ldexp_f32 v16, v16, v18
	v_log_f32_e32 v16, v16
	s_nop 0
	v_mul_f32_e32 v18, 0x3f317217, v16
	v_fma_f32 v18, v16, s5, -v18
	v_fmac_f32_e32 v18, 0x3377d1cf, v16
	v_fmac_f32_e32 v18, 0x3f317217, v16
	v_cmp_lt_f32_e64 s[10:11], |v16|, s6
	s_nop 1
	v_cndmask_b32_e64 v16, v16, v18, s[10:11]
	v_cndmask_b32_e32 v18, 0, v222, vcc
	v_sub_f32_e32 v19, v16, v18
	v_mul_f32_e64 v18, |v53|, s4
	v_exp_f32_e32 v18, v18
	v_min_f32_e32 v16, 0, v53
	v_add_f32_e32 v18, 1.0, v18
	v_cmp_gt_f32_e32 vcc, s0, v18
	s_mov_b32 s0, 0x3d800000
	s_nop 0
	v_cndmask_b32_e64 v53, 0, 32, vcc
	v_ldexp_f32 v18, v18, v53
	v_log_f32_e32 v18, v18
	s_nop 0
	v_mul_f32_e32 v53, 0x3f317217, v18
	v_fma_f32 v53, v18, s5, -v53
	v_fmac_f32_e32 v53, 0x3377d1cf, v18
	v_fmac_f32_e32 v53, 0x3f317217, v18
	v_cmp_lt_f32_e64 s[10:11], |v18|, s6
	s_nop 1
	v_cndmask_b32_e64 v18, v18, v53, s[10:11]
	v_cndmask_b32_e32 v53, 0, v222, vcc
	v_sub_f32_e32 v18, v18, v53
	v_pk_add_f32 v[16:17], v[16:17], v[18:19] neg_lo:[0,1] neg_hi:[0,1]
	s_nop 0
	v_pk_mul_f32 v[54:55], v[16:17], s[0:1] op_sel_hi:[1,0]
; template <bool FINAL>
; DI void gla_unit(KA a, int l, int item, LAS unsigned char* lds) {
;     ...
;         for (int jj = 0; jj < 8; ++jj) {
;             const int t = 8 * tg + jj;
;             float ga = 0.f, gb = 0.f;
;             if (t < nvalid) {
;                 const u32x4* lp = (const u32x4*)(U + (size_t)(row0 + t) * UN + U_LR);
;                 float lr[16]; unpack8(lp[0], lr); unpack8(lp[1], lr + 8);
;                 float za = bg[0], zb = bg[1];
; #pragma unroll
;                 for (int e = 0; e < 16; ++e) { za += wg[0][e] * lr[e]; zb += wg[1][e] * lr[e]; }
;                 ga = (fminf(za, 0.f) - __logf(1.f + __expf(-fabsf(za)))) * (1.f / 16.f);
;                 gb = (fminf(zb, 0.f) - __logf(1.f + __expf(-fabsf(zb)))) * (1.f / 16.f);
;             }
;             run0 += ga; run1 += gb; bl[0][jj] = run0; bl[1][jj] = run1;
;         }
.LBB0_663:
	s_and_b64 vcc, exec, s[8:9]
	v_mov_b32_e32 v53, 0
	s_cbranch_vccnz .LBB0_665
	s_add_i32 s0, s52, s51
	s_mul_hi_i32 s5, s0, 0x1600
	s_mulk_i32 s0, 0x1600
	s_add_u32 s4, s34, s0
	s_addc_u32 s5, s35, s5
	s_add_u32 s6, s4, 0x1400
	s_addc_u32 s7, s5, 0
	s_mov_b32 s4, 0xbfb8aa3b
	s_mov_b32 s0, 0x800000
	s_mov_b32 s5, 0x3f317217
	s_mov_b32 s6, 0x7f800000
	s_waitcnt vmcnt(0)
	v_mov_b32_e32 v124, v196
	v_mov_b32_e32 v125, v197
	v_mov_b32_e32 v126, v198
	v_mov_b32_e32 v127, v199
	v_mov_b32_e32 v16, v200
	v_mov_b32_e32 v17, v201
	v_mov_b32_e32 v18, v202
	v_mov_b32_e32 v19, v203
	v_lshlrev_b32_e32 v52, 16, v124
	v_and_b32_e32 v53, 0xffff0000, v124
	v_fmac_f32_e32 v113, v112, v52
	v_lshlrev_b32_e32 v123, 16, v125
	v_fmac_f32_e32 v113, v111, v53
	v_and_b32_e32 v124, 0xffff0000, v125
	v_fmac_f32_e32 v122, v118, v52
	v_fmac_f32_e32 v113, v110, v123
	v_lshlrev_b32_e32 v125, 16, v126
	v_fmac_f32_e32 v122, v117, v53
	v_fmac_f32_e32 v113, v109, v124
	v_and_b32_e32 v126, 0xffff0000, v126
	v_fmac_f32_e32 v122, v116, v123
	v_fmac_f32_e32 v113, v115, v125
	v_and_b32_e32 v52, 0xffff0000, v127
	v_lshlrev_b32_e32 v53, 16, v127
	v_fmac_f32_e32 v122, v121, v124
	v_fmac_f32_e32 v113, v114, v126
	v_pk_mul_f32 v[32:33], v[32:33], v[52:53]
	v_fmac_f32_e32 v122, v120, v125
	v_add_f32_e32 v33, v33, v113
	v_fmac_f32_e32 v122, v119, v126
	v_add_f32_e32 v109, v32, v33
	v_pk_mul_f32 v[32:33], v[40:41], v[52:53]
	s_nop 0
	v_add_f32_e32 v33, v33, v122
	v_add_f32_e32 v40, v32, v33
	v_and_b32_e32 v32, 0xffff0000, v16
	v_lshlrev_b32_e32 v33, 16, v16
	v_pk_mul_f32 v[30:31], v[30:31], v[32:33]
	s_nop 0
	v_add_f32_e32 v16, v31, v109
	v_add_f32_e32 v41, v30, v16
	v_pk_mul_f32 v[30:31], v[38:39], v[32:33]
	s_nop 0
	v_add_f32_e32 v16, v31, v40
	v_add_f32_e32 v30, v30, v16
	v_and_b32_e32 v16, 0xffff0000, v17
	v_lshlrev_b32_e32 v17, 16, v17
	v_pk_mul_f32 v[26:27], v[26:27], v[16:17]
	v_pk_mul_f32 v[16:17], v[36:37], v[16:17]
	v_add_f32_e32 v27, v27, v41
	v_add_f32_e32 v17, v17, v30
	v_add_f32_e32 v26, v26, v27
	v_add_f32_e32 v27, v16, v17
	v_and_b32_e32 v16, 0xffff0000, v18
	v_lshlrev_b32_e32 v17, 16, v18
	v_pk_mul_f32 v[24:25], v[24:25], v[16:17]
	v_pk_mul_f32 v[16:17], v[34:35], v[16:17]
	v_add_f32_e32 v18, v25, v26
	v_add_f32_e32 v17, v17, v27
	v_add_f32_e32 v25, v16, v17
	v_and_b32_e32 v16, 0xffff0000, v19
	v_lshlrev_b32_e32 v17, 16, v19
	v_add_f32_e32 v24, v24, v18
	v_pk_mul_f32 v[18:19], v[22:23], v[16:17]
	v_pk_mul_f32 v[16:17], v[28:29], v[16:17]
	v_add_f32_e32 v19, v19, v24
	v_add_f32_e32 v18, v18, v19
	v_add_f32_e32 v17, v17, v25
	v_add_f32_e32 v22, v16, v17
	v_mul_f32_e64 v16, |v18|, s4
	v_exp_f32_e32 v16, v16
	v_min_f32_e32 v17, 0, v18
	v_add_f32_e32 v16, 1.0, v16
	v_cmp_gt_f32_e32 vcc, s0, v16
	s_nop 1
	v_cndmask_b32_e64 v18, 0, 32, vcc
	v_ldexp_f32 v16, v16, v18
	v_log_f32_e32 v16, v16
	s_nop 0
	v_mul_f32_e32 v18, 0x3f317217, v16
	v_fma_f32 v18, v16, s5, -v18
	v_fmac_f32_e32 v18, 0x3377d1cf, v16
	v_fmac_f32_e32 v18, 0x3f317217, v16
	v_cmp_lt_f32_e64 s[8:9], |v16|, s6
	s_nop 1
	v_cndmask_b32_e64 v16, v16, v18, s[8:9]
	v_cndmask_b32_e32 v18, 0, v222, vcc
	v_sub_f32_e32 v19, v16, v18
	v_mul_f32_e64 v18, |v22|, s4
	v_exp_f32_e32 v18, v18
	v_min_f32_e32 v16, 0, v22
	v_add_f32_e32 v18, 1.0, v18
	v_cmp_gt_f32_e32 vcc, s0, v18
	s_mov_b32 s0, 0x3d800000
	s_nop 0
	v_cndmask_b32_e64 v22, 0, 32, vcc
	v_ldexp_f32 v18, v18, v22
	v_log_f32_e32 v18, v18
	s_nop 0
	v_mul_f32_e32 v22, 0x3f317217, v18
	v_fma_f32 v22, v18, s5, -v22
	v_fmac_f32_e32 v22, 0x3377d1cf, v18
	v_fmac_f32_e32 v22, 0x3f317217, v18
	v_cmp_lt_f32_e64 s[8:9], |v18|, s6
	s_nop 1
	v_cndmask_b32_e64 v18, v18, v22, s[8:9]
	v_cndmask_b32_e32 v22, 0, v222, vcc
	v_sub_f32_e32 v18, v18, v22
	v_pk_add_f32 v[16:17], v[16:17], v[18:19] neg_lo:[0,1] neg_hi:[0,1]
	s_nop 0
	v_pk_mul_f32 v[52:53], v[16:17], s[0:1] op_sel_hi:[1,0]

; template <bool FINAL>
; DI void gla_unit(KA a, int l, int item, LAS unsigned char* lds) {
;     ...
;     for (int hh = 0; hh < 2; ++hh) {
;         const int hd = 2 * hp + hh;
; #pragma unroll
;         for (int jj = 0; jj < 8; ++jj) {
;             const int t = 8 * tg + jj; kraw[hh][jj] = 0u; qraw[hh][jj] = 0u;
;             if (t < nvalid) { kraw[hh][jj] = U[(size_t)(row0 + t) * UN + U_K + hd * 64 + dk]; if (FINAL) qraw[hh][jj] = U[(size_t)(row0 + t) * UN + U_Q + hd * 64 + dk]; }
;         }
;         v0[hh] = (u32x4){0u, 0u, 0u, 0u}; v1[hh] = v0[hh]; g0[hh] = v0[hh]; g1[hh] = v0[hh];
;         if (vj < nvalid) {
;             const u32x4* vp = (const u32x4*)(U + (size_t)(row0 + vj) * UN + U_V + hd * 128 + vdvc); v0[hh] = vp[0]; v1[hh] = vp[1];
;             if (FINAL) { const u32x4* gp = (const u32x4*)(U + (size_t)(row0 + vj) * UN + U_GO + hd * 128 + vdvc); g0[hh] = gp[0]; g1[hh] = gp[1]; }
;         }
.LBB0_796:
	v_mov_b32_e32 v123, v212
	s_load_dwordx2 s[28:29], s[2:3], 0xd8
	s_and_b32 s21, s62, 1
	v_readfirstlane_b32 s44, v123
	s_lshl_b32 s54, s21, 7
	s_ashr_i32 s43, s44, 6
	s_waitcnt lgkmcnt(0)
	s_add_u32 s30, s28, 0x5000000
	s_addc_u32 s31, s29, 0
	s_lshl_b32 s53, s43, 3
	s_cmp_lt_i32 s53, s0
	v_and_b32_e32 v85, 63, v123
	v_mov_b32_e32 v136, 0
	s_cselect_b64 s[6:7], -1, 0
	s_cmp_ge_i32 s53, s0
	v_mov_b32_e32 v140, 0
	v_mov_b32_e32 v139, 0
	s_cbranch_scc1 .LBB0_798
	s_add_i32 s8, s53, s46
	s_mul_hi_i32 s9, s8, 0x1600
	s_mulk_i32 s8, 0x1600
	s_add_u32 s8, s30, s8
	s_addc_u32 s9, s31, s9
	s_lshl_b32 s12, s54, 1
	s_add_u32 s8, s8, s12
	s_addc_u32 s9, s9, 0
	v_lshlrev_b32_e32 v0, 1, v85
	global_load_short_d16_hi v139, v0, s[8:9] offset:2560
	s_nop 0
	global_load_short_d16_hi v140, v0, s[8:9] offset:2048
.LBB0_798:
	s_or_b32 s45, s53, 1
	s_cmp_lt_i32 s45, s0
	s_cselect_b64 s[12:13], -1, 0
	s_cmp_ge_i32 s45, s0
	v_mov_b32_e32 v137, 0
	s_cbranch_scc1 .LBB0_800
	s_add_i32 s8, s45, s46
	s_mul_hi_i32 s9, s8, 0x1600
	s_mulk_i32 s8, 0x1600
	s_add_u32 s8, s30, s8
	s_addc_u32 s9, s31, s9
	s_lshl_b32 s14, s54, 1
	s_add_u32 s8, s8, s14
	s_addc_u32 s9, s9, 0
	v_lshlrev_b32_e32 v0, 1, v85
	global_load_short_d16_hi v137, v0, s[8:9] offset:2560
	s_nop 0
	global_load_short_d16_hi v136, v0, s[8:9] offset:2048
.LBB0_800:
	s_or_b32 s52, s53, 2
	s_cmp_lt_i32 s52, s0
	v_mov_b32_e32 v132, 0
	s_cselect_b64 s[14:15], -1, 0
	s_cmp_ge_i32 s52, s0
	v_mov_b32_e32 v138, 0
	v_mov_b32_e32 v134, 0
	s_cbranch_scc1 .LBB0_802
	s_add_i32 s8, s52, s46
	s_mul_hi_i32 s9, s8, 0x1600
	s_mulk_i32 s8, 0x1600
	s_add_u32 s8, s30, s8
	s_addc_u32 s9, s31, s9
	s_lshl_b32 s16, s54, 1
	s_add_u32 s8, s8, s16
	s_addc_u32 s9, s9, 0
	v_lshlrev_b32_e32 v0, 1, v85
	global_load_short_d16_hi v134, v0, s[8:9] offset:2560
	s_nop 0
	global_load_short_d16_hi v138, v0, s[8:9] offset:2048
.LBB0_802:
	s_or_b32 s51, s53, 3
	s_cmp_lt_i32 s51, s0
	s_cselect_b64 s[16:17], -1, 0
	s_cmp_ge_i32 s51, s0
	v_mov_b32_e32 v133, 0
	s_cbranch_scc1 .LBB0_804
	s_add_i32 s8, s51, s46
	s_mul_hi_i32 s9, s8, 0x1600
	s_mulk_i32 s8, 0x1600
	s_add_u32 s8, s30, s8
	s_addc_u32 s9, s31, s9
	s_lshl_b32 s18, s54, 1
	s_add_u32 s8, s8, s18
	s_addc_u32 s9, s9, 0
	v_lshlrev_b32_e32 v0, 1, v85
	global_load_short_d16_hi v133, v0, s[8:9] offset:2560
	s_nop 0
	global_load_short_d16_hi v132, v0, s[8:9] offset:2048
.LBB0_804:
	s_or_b32 s50, s53, 4
	s_cmp_lt_i32 s50, s0
	v_mov_b32_e32 v128, 0
	s_cselect_b64 s[34:35], -1, 0
	s_cmp_ge_i32 s50, s0
	v_mov_b32_e32 v135, 0
	v_mov_b32_e32 v130, 0
	s_cbranch_scc1 .LBB0_806
	s_add_i32 s8, s50, s46
	s_mul_hi_i32 s9, s8, 0x1600
	s_mulk_i32 s8, 0x1600
	s_add_u32 s8, s30, s8
	s_addc_u32 s9, s31, s9
	s_lshl_b32 s18, s54, 1
	s_add_u32 s8, s8, s18
	s_addc_u32 s9, s9, 0
	v_lshlrev_b32_e32 v0, 1, v85
	global_load_short_d16_hi v130, v0, s[8:9] offset:2560
	s_nop 0
	global_load_short_d16_hi v135, v0, s[8:9] offset:2048
.LBB0_806:
	s_or_b32 s49, s53, 5
	s_cmp_lt_i32 s49, s0
	s_cselect_b64 s[36:37], -1, 0
	s_cmp_ge_i32 s49, s0
	v_mov_b32_e32 v129, 0
	s_cbranch_scc1 .LBB0_808
	s_add_i32 s8, s49, s46
	s_mul_hi_i32 s9, s8, 0x1600
	s_mulk_i32 s8, 0x1600
	s_add_u32 s8, s30, s8
	s_addc_u32 s9, s31, s9
	s_lshl_b32 s18, s54, 1
	s_add_u32 s8, s8, s18
	s_addc_u32 s9, s9, 0
	v_lshlrev_b32_e32 v0, 1, v85
	global_load_short_d16_hi v129, v0, s[8:9] offset:2560
	s_nop 0
	global_load_short_d16_hi v128, v0, s[8:9] offset:2048
.LBB0_808:
	s_or_b32 s48, s53, 6
	s_cmp_lt_i32 s48, s0
	v_mov_b32_e32 v125, 0
	s_cselect_b64 s[38:39], -1, 0
	s_cmp_ge_i32 s48, s0
	v_mov_b32_e32 v131, 0
	v_mov_b32_e32 v127, 0
	s_cbranch_scc1 .LBB0_810
	s_add_i32 s8, s48, s46
	s_mul_hi_i32 s9, s8, 0x1600
	s_mulk_i32 s8, 0x1600
	s_add_u32 s8, s30, s8
	s_addc_u32 s9, s31, s9
	s_lshl_b32 s18, s54, 1
	s_add_u32 s8, s8, s18
	s_addc_u32 s9, s9, 0
	v_lshlrev_b32_e32 v0, 1, v85
	global_load_short_d16_hi v127, v0, s[8:9] offset:2560
	s_nop 0
	global_load_short_d16_hi v131, v0, s[8:9] offset:2048
.LBB0_810:
	s_or_b32 s47, s53, 7
	s_cmp_lt_i32 s47, s0
	s_cselect_b64 s[40:41], -1, 0
	s_cmp_ge_i32 s47, s0
	v_mov_b32_e32 v126, 0
	s_cbranch_scc1 .LBB0_812
	s_add_i32 s8, s47, s46
	s_mul_hi_i32 s9, s8, 0x1600
	s_mulk_i32 s8, 0x1600
	s_add_u32 s8, s30, s8
	s_addc_u32 s9, s31, s9
	s_lshl_b32 s18, s54, 1
	s_add_u32 s8, s8, s18
	s_addc_u32 s9, s9, 0
	v_lshlrev_b32_e32 v0, 1, v85
	global_load_short_d16_hi v126, v0, s[8:9] offset:2560
	s_nop 0
	global_load_short_d16_hi v125, v0, s[8:9] offset:2048
.LBB0_812:
	v_ashrrev_i32_e32 v122, 3, v123
	v_lshlrev_b32_e32 v0, 4, v123
	v_and_b32_e32 v167, 0x70, v0
	v_add_u32_e32 v84, s46, v122
	v_mov_b64_e32 v[0:1], s[30:31]
	v_mad_i64_i32 v[0:1], s[18:19], v84, s64, v[0:1]
	v_lshlrev_b32_e32 v144, 1, v167
	v_lshl_add_u64 v[32:33], v[0:1], 0, v[144:145]
	s_mov_b64 s[18:19], 0x1000
	v_cmp_gt_i32_e64 s[8:9], s0, v122
	v_lshl_add_u64 v[34:35], v[32:33], 0, s[18:19]
	s_lshl_b32 s42, s21, 8
	v_mov_b32_e32 v0, 0
	v_mov_b32_e32 v36, 0
	v_mov_b32_e32 v37, 0
	v_mov_b32_e32 v38, 0
	v_mov_b32_e32 v39, 0
	v_mov_b32_e32 v40, 0
	v_mov_b32_e32 v41, 0
	v_mov_b32_e32 v42, 0
	v_mov_b32_e32 v43, 0
	v_mov_b32_e32 v1, 0
	v_mov_b32_e32 v2, 0
	v_mov_b32_e32 v3, 0
	v_mov_b32_e32 v4, 0
	v_mov_b32_e32 v5, 0
	v_mov_b32_e32 v6, 0
	v_mov_b32_e32 v7, 0
	s_and_saveexec_b64 s[18:19], s[8:9]
	s_cbranch_execz .LBB0_814
	s_lshl_b32 s0, s42, 1
	v_lshl_add_u64 v[0:1], v[32:33], 0, s[0:1]
	v_lshl_add_u64 v[8:9], v[34:35], 0, s[0:1]
	global_load_dwordx4 v[4:7], v[0:1], off offset:3072
	s_nop 0
	global_load_dwordx4 v[0:3], v[0:1], off offset:3088
	s_nop 0
	global_load_dwordx4 v[36:39], v[8:9], off offset:16
	global_load_dwordx4 v[40:43], v[8:9], off

; DI float bf2f(unsigned v) { return __uint_as_float(v << 16); }
; template <bool FINAL>
; DI void gla_unit(KA a, int l, int item, LAS unsigned char* lds) {
;     ...
;         S0[hh] = nullptr;
;         if (!u.prompt) S0[hh] = a->in[4] + (size_t)((l * NSB + u.s) * 4 + hd) * 8192;
;         if (FINAL) {
;             const bf16_t* Sb = (u.prompt && u.c > 0) ? (const bf16_t*)(a->ws + WS_SB) + (size_t)(unit * 4 + hd) * 8192 : nullptr;
; #pragma unroll
;             for (int it = 0; it < 4; ++it) {
;                 const int idx = it * 512 + tid; sv[hh][it] = (f32x4){0.f, 0.f, 0.f, 0.f};
;                 if (S0[hh]) sv[hh][it] = *(const f32x4*)(S0[hh] + (idx >> 5) * 128 + (idx & 31) * 4);
;                 else if (Sb) { const u32x2 v = *(const u32x2*)(Sb + (idx >> 5) * 128 + (idx & 31) * 4); sv[hh][it] = (f32x4){bf2f(v.x & 0xffffu), __uint_as_float(v.x & 0xffff0000u), bf2f(v.y & 0xffffu), __uint_as_float(v.y & 0xffff0000u)}; }
;             }
.LBB0_816:
	s_add_u32 s57, s28, 0xd200000
	s_addc_u32 s58, s29, 0
	s_lshl_b32 s0, s55, 16
	s_lshl_b32 s18, s21, 15
	s_or_b32 s0, s18, s0
	s_add_u32 s0, s57, s0
	s_addc_u32 s18, s58, 0
	v_lshlrev_b32_e32 v169, 2, v123
	s_and_b64 s[10:11], s[10:11], exec
	v_and_b32_e32 v168, 0x7c, v169
	s_cselect_b32 s11, s18, 0
	s_cselect_b32 s10, s0, 0
	s_cmp_lg_u64 s[22:23], 0
	s_cselect_b64 s[20:21], -1, 0
	s_cmp_lg_u64 s[10:11], 0
	v_lshlrev_b32_e32 v54, 2, v168
	v_mov_b32_e32 v55, v145
	s_cselect_b64 s[18:19], -1, 0
	s_mov_b64 s[66:67], s[18:19]
	s_cmp_eq_u64 s[22:23], 0
	v_lshl_add_u64 v[20:21], s[22:23], 0, v[54:55]
	s_cbranch_scc1 .LBB0_818
	v_and_b32_e32 v8, 0xffffff80, v169
	v_ashrrev_i32_e32 v9, 31, v8
	v_lshl_add_u64 v[8:9], v[8:9], 2, v[20:21]
	global_load_dwordx4 v[8:11], v[8:9], off
	s_mov_b64 s[22:23], 0
	s_branch .LBB0_819

; DI float bf2f(unsigned v) { return __uint_as_float(v << 16); }
; template <bool FINAL>
; DI void gla_unit(KA a, int l, int item, LAS unsigned char* lds) {
;     ...
;             for (int it = 0; it < 4; ++it) {
;                 const int idx = it * 512 + tid; sv[hh][it] = (f32x4){0.f, 0.f, 0.f, 0.f};
;                 if (S0[hh]) sv[hh][it] = *(const f32x4*)(S0[hh] + (idx >> 5) * 128 + (idx & 31) * 4);
;                 else if (Sb) { const u32x2 v = *(const u32x2*)(Sb + (idx >> 5) * 128 + (idx & 31) * 4); sv[hh][it] = (f32x4){bf2f(v.x & 0xffffu), __uint_as_float(v.x & 0xffff0000u), bf2f(v.y & 0xffffu), __uint_as_float(v.y & 0xffff0000u)}; }
;             }
.LBB0_819:
	v_lshlrev_b32_e32 v52, 1, v168
	v_mov_b32_e32 v53, v145
	s_andn2_b64 vcc, exec, s[22:23]
	v_lshl_add_u64 v[24:25], s[10:11], 0, v[52:53]
	s_cbranch_vccnz .LBB0_823
	s_andn2_b64 vcc, exec, s[18:19]
	s_cbranch_vccnz .LBB0_822
	v_and_b32_e32 v8, 0xffffff80, v169
	v_ashrrev_i32_e32 v9, 31, v8
	v_lshl_add_u64 v[8:9], v[8:9], 1, v[24:25]
	global_load_dwordx2 v[10:11], v[8:9], off
	s_branch .LBB0_823

; DI float bf2f(unsigned v) { return __uint_as_float(v << 16); }
; template <bool FINAL>
; DI void gla_unit(KA a, int l, int item, LAS unsigned char* lds) {
;     ...
;             for (int it = 0; it < 4; ++it) {
;                 const int idx = it * 512 + tid; sv[hh][it] = (f32x4){0.f, 0.f, 0.f, 0.f};
;                 if (S0[hh]) sv[hh][it] = *(const f32x4*)(S0[hh] + (idx >> 5) * 128 + (idx & 31) * 4);
;                 else if (Sb) { const u32x2 v = *(const u32x2*)(Sb + (idx >> 5) * 128 + (idx & 31) * 4); sv[hh][it] = (f32x4){bf2f(v.x & 0xffffu), __uint_as_float(v.x & 0xffff0000u), bf2f(v.y & 0xffffu), __uint_as_float(v.y & 0xffff0000u)}; }
;             }
.LBB0_829:
.LBB0_830:
	s_andn2_b64 vcc, exec, s[18:19]
	s_cbranch_vccnz .LBB0_838
	v_lshlrev_b32_e32 v12, 2, v170
	v_and_b32_e32 v12, 0xffffff80, v12
	v_ashrrev_i32_e32 v13, 31, v12
	v_lshl_add_u64 v[12:13], v[12:13], 1, v[24:25]
	global_load_dwordx2 v[14:15], v[12:13], off
	s_and_b64 vcc, exec, s[10:11]
	v_add_u32_e32 v171, 0x400, v123
	s_cbranch_vccz .LBB0_826
.LBB0_832:
.LBB0_833:
	s_andn2_b64 vcc, exec, s[18:19]
	s_cbranch_vccnz .LBB0_839
	v_lshlrev_b32_e32 v16, 2, v171
	v_and_b32_e32 v16, 0xffffff80, v16
	v_ashrrev_i32_e32 v17, 31, v16
	v_lshl_add_u64 v[16:17], v[16:17], 1, v[24:25]
	global_load_dwordx2 v[18:19], v[16:17], off
	s_and_b64 vcc, exec, s[10:11]
	v_add_u32_e32 v172, 0x600, v123
	s_cbranch_vccz .LBB0_828
.LBB0_835:
.LBB0_836:
	s_andn2_b64 vcc, exec, s[18:19]
	s_cbranch_vccnz .LBB0_840
	v_lshlrev_b32_e32 v20, 2, v172
	v_and_b32_e32 v20, 0xffffff80, v20
	v_ashrrev_i32_e32 v21, 31, v20
	v_lshl_add_u64 v[20:21], v[20:21], 1, v[24:25]
	global_load_dwordx2 v[22:23], v[20:21], off
	s_branch .LBB0_841

; template <bool FINAL>
; DI void gla_unit(KA a, int l, int item, LAS unsigned char* lds) {
;     ...
;     for (int hh = 0; hh < 2; ++hh) {
;         const int hd = 2 * hp + hh;
; #pragma unroll
;         for (int jj = 0; jj < 8; ++jj) {
;             const int t = 8 * tg + jj; kraw[hh][jj] = 0u; qraw[hh][jj] = 0u;
;             if (t < nvalid) { kraw[hh][jj] = U[(size_t)(row0 + t) * UN + U_K + hd * 64 + dk]; if (FINAL) qraw[hh][jj] = U[(size_t)(row0 + t) * UN + U_Q + hd * 64 + dk]; }
;         }
.LBB0_841:
	s_or_b32 s59, s24, 1
	v_cndmask_b32_e64 v24, 0, 1, s[6:7]
	s_lshl_b32 s0, s59, 6
	v_mov_b32_e32 v141, 0
	v_cmp_ne_u32_e64 s[24:25], 1, v24
	s_andn2_b64 vcc, exec, s[6:7]
	v_mov_b32_e32 v154, 0
	v_mov_b32_e32 v142, 0
	s_cbranch_vccnz .LBB0_843
	s_add_i32 s6, s53, s46
	s_mul_hi_i32 s7, s6, 0x1600
	s_mulk_i32 s6, 0x1600
	s_add_u32 s6, s30, s6
	s_addc_u32 s7, s31, s7
	s_lshl_b32 s10, s0, 1
	s_add_u32 s6, s6, s10
	s_addc_u32 s7, s7, 0
	v_lshlrev_b32_e32 v24, 1, v85
	global_load_short_d16_hi v142, v24, s[6:7] offset:2560
	s_nop 0
	global_load_short_d16_hi v154, v24, s[6:7] offset:2048
.LBB0_843:
	v_cndmask_b32_e64 v24, 0, 1, s[12:13]
	v_cmp_ne_u32_e64 s[22:23], 1, v24
	s_andn2_b64 vcc, exec, s[12:13]
	v_mov_b32_e32 v155, 0
	s_cbranch_vccnz .LBB0_845
	s_add_i32 s6, s45, s46
	s_mul_hi_i32 s7, s6, 0x1600
	s_mulk_i32 s6, 0x1600
	s_add_u32 s6, s30, s6
	s_addc_u32 s7, s31, s7
	s_lshl_b32 s10, s0, 1
	s_add_u32 s6, s6, s10
	s_addc_u32 s7, s7, 0
	v_lshlrev_b32_e32 v24, 1, v85
	global_load_short_d16_hi v155, v24, s[6:7] offset:2560
	s_nop 0
	global_load_short_d16_hi v141, v24, s[6:7] offset:2048
.LBB0_845:
	v_cndmask_b32_e64 v24, 0, 1, s[14:15]
	v_mov_b32_e32 v143, 0
	v_cmp_ne_u32_e64 s[20:21], 1, v24
	s_andn2_b64 vcc, exec, s[14:15]
	v_mov_b32_e32 v157, 0
	v_mov_b32_e32 v156, 0
	s_cbranch_vccnz .LBB0_847
	s_add_i32 s6, s52, s46
	s_mul_hi_i32 s7, s6, 0x1600
	s_mulk_i32 s6, 0x1600
	s_add_u32 s6, s30, s6
	s_addc_u32 s7, s31, s7
	s_lshl_b32 s10, s0, 1
	s_add_u32 s6, s6, s10
	s_addc_u32 s7, s7, 0
	v_lshlrev_b32_e32 v24, 1, v85
	global_load_short_d16_hi v156, v24, s[6:7] offset:2560
	s_nop 0
	global_load_short_d16_hi v157, v24, s[6:7] offset:2048
.LBB0_847:
	v_cndmask_b32_e64 v24, 0, 1, s[16:17]
	v_cmp_ne_u32_e64 s[18:19], 1, v24
	s_andn2_b64 vcc, exec, s[16:17]
	v_mov_b32_e32 v158, 0
	s_cbranch_vccnz .LBB0_849
	s_add_i32 s6, s51, s46
	s_mul_hi_i32 s7, s6, 0x1600
	s_mulk_i32 s6, 0x1600
	s_add_u32 s6, s30, s6
	s_addc_u32 s7, s31, s7
	s_lshl_b32 s10, s0, 1
	s_add_u32 s6, s6, s10
	s_addc_u32 s7, s7, 0
	v_lshlrev_b32_e32 v24, 1, v85
	global_load_short_d16_hi v158, v24, s[6:7] offset:2560
	s_nop 0
	global_load_short_d16_hi v143, v24, s[6:7] offset:2048
.LBB0_849:
	v_cndmask_b32_e64 v24, 0, 1, s[34:35]
	v_mov_b32_e32 v159, 0
	v_cmp_ne_u32_e64 s[16:17], 1, v24
	s_andn2_b64 vcc, exec, s[34:35]
	v_mov_b32_e32 v161, 0
	v_mov_b32_e32 v160, 0
	s_cbranch_vccnz .LBB0_851
	s_add_i32 s6, s50, s46
	s_mul_hi_i32 s7, s6, 0x1600
	s_mulk_i32 s6, 0x1600
	s_add_u32 s6, s30, s6
	s_addc_u32 s7, s31, s7
	s_lshl_b32 s10, s0, 1
	s_add_u32 s6, s6, s10
	s_addc_u32 s7, s7, 0
	v_lshlrev_b32_e32 v24, 1, v85
	global_load_short_d16_hi v160, v24, s[6:7] offset:2560
	s_nop 0
	global_load_short_d16_hi v161, v24, s[6:7] offset:2048
.LBB0_851:
	v_cndmask_b32_e64 v24, 0, 1, s[36:37]
	v_cmp_ne_u32_e64 s[14:15], 1, v24
	s_andn2_b64 vcc, exec, s[36:37]
	v_mov_b32_e32 v162, 0
	s_cbranch_vccnz .LBB0_853
	s_add_i32 s6, s49, s46
	s_mul_hi_i32 s7, s6, 0x1600
	s_mulk_i32 s6, 0x1600
	s_add_u32 s6, s30, s6
	s_addc_u32 s7, s31, s7
	s_lshl_b32 s10, s0, 1
	s_add_u32 s6, s6, s10
	s_addc_u32 s7, s7, 0
	v_lshlrev_b32_e32 v24, 1, v85
	global_load_short_d16_hi v162, v24, s[6:7] offset:2560
	s_nop 0
	global_load_short_d16_hi v159, v24, s[6:7] offset:2048
.LBB0_853:
	v_cndmask_b32_e64 v24, 0, 1, s[38:39]
	v_mov_b32_e32 v163, 0
	v_cmp_ne_u32_e64 s[12:13], 1, v24
	s_andn2_b64 vcc, exec, s[38:39]
	v_mov_b32_e32 v165, 0
	v_mov_b32_e32 v164, 0
	s_cbranch_vccnz .LBB0_855
	s_add_i32 s6, s48, s46
	s_mul_hi_i32 s7, s6, 0x1600
	s_mulk_i32 s6, 0x1600
	s_add_u32 s6, s30, s6
	s_addc_u32 s7, s31, s7
	s_lshl_b32 s10, s0, 1
	s_add_u32 s6, s6, s10
	s_addc_u32 s7, s7, 0
	v_lshlrev_b32_e32 v24, 1, v85
	global_load_short_d16_hi v164, v24, s[6:7] offset:2560
	s_nop 0
	global_load_short_d16_hi v165, v24, s[6:7] offset:2048
.LBB0_855:
	v_cndmask_b32_e64 v24, 0, 1, s[40:41]
	v_cmp_ne_u32_e64 s[10:11], 1, v24
	s_andn2_b64 vcc, exec, s[40:41]
	v_mov_b32_e32 v166, 0
	s_cbranch_vccnz .LBB0_857
	s_add_i32 s6, s47, s46
	s_mul_hi_i32 s7, s6, 0x1600
	s_mulk_i32 s6, 0x1600
	s_add_u32 s6, s30, s6
	s_addc_u32 s7, s31, s7
	s_lshl_b32 s0, s0, 1
	s_add_u32 s6, s6, s0
	s_addc_u32 s7, s7, 0
	v_lshlrev_b32_e32 v24, 1, v85
	global_load_short_d16_hi v166, v24, s[6:7] offset:2560
	s_nop 0
	global_load_short_d16_hi v163, v24, s[6:7] offset:2048

; DI float bf2f(unsigned v) { return __uint_as_float(v << 16); }
; template <bool FINAL>
; DI void gla_unit(KA a, int l, int item, LAS unsigned char* lds) {
;     ...
;         S0[hh] = nullptr;
;         if (!u.prompt) S0[hh] = a->in[4] + (size_t)((l * NSB + u.s) * 4 + hd) * 8192;
;         if (FINAL) {
;             const bf16_t* Sb = (u.prompt && u.c > 0) ? (const bf16_t*)(a->ws + WS_SB) + (size_t)(unit * 4 + hd) * 8192 : nullptr;
; #pragma unroll
;             for (int it = 0; it < 4; ++it) {
;                 const int idx = it * 512 + tid; sv[hh][it] = (f32x4){0.f, 0.f, 0.f, 0.f};
;                 if (S0[hh]) sv[hh][it] = *(const f32x4*)(S0[hh] + (idx >> 5) * 128 + (idx & 31) * 4);
;                 else if (Sb) { const u32x2 v = *(const u32x2*)(Sb + (idx >> 5) * 128 + (idx & 31) * 4); sv[hh][it] = (f32x4){bf2f(v.x & 0xffffu), __uint_as_float(v.x & 0xffff0000u), bf2f(v.y & 0xffffu), __uint_as_float(v.y & 0xffff0000u)}; }
;             }
.LBB0_861:
	s_lshl_b32 s0, s55, 15
	s_lshl_b32 s0, s0, 1
	s_lshl_b32 s6, s59, 14
	s_or_b32 s0, s6, s0
	s_add_u32 s0, s57, s0
	s_addc_u32 s6, s58, 0
	s_and_b64 s[4:5], s[4:5], exec
	s_cselect_b32 s27, s6, 0
	s_cselect_b32 s26, s0, 0
	s_cmp_lg_u64 s[34:35], 0
	s_cselect_b64 s[6:7], -1, 0
	s_cmp_lg_u64 s[26:27], 0
	v_mov_b32_e32 v55, v145
	s_cselect_b64 s[4:5], -1, 0
	s_mov_b64 s[68:69], s[4:5]
	s_cmp_eq_u64 s[34:35], 0
	v_lshl_add_u64 v[34:35], s[34:35], 0, v[54:55]
	s_cbranch_scc1 .LBB0_869
	v_and_b32_e32 v32, 0xffffff80, v169
	v_ashrrev_i32_e32 v33, 31, v32
	v_lshl_add_u64 v[32:33], v[32:33], 2, v[34:35]
	global_load_dwordx4 v[64:67], v[32:33], off
	v_mov_b32_e32 v53, v145
	v_lshl_add_u64 v[32:33], s[26:27], 0, v[52:53]
	s_cbranch_execz .LBB0_870
	v_cndmask_b32_e64 v52, 0, 1, s[6:7]
	v_cmp_ne_u32_e64 s[26:27], 1, v52
	s_andn2_b64 vcc, exec, s[6:7]
	s_cbranch_vccnz .LBB0_872

; DI float bf2f(unsigned v) { return __uint_as_float(v << 16); }
; template <bool FINAL>
; DI void gla_unit(KA a, int l, int item, LAS unsigned char* lds) {
;     ...
;             for (int it = 0; it < 4; ++it) {
;                 const int idx = it * 512 + tid; sv[hh][it] = (f32x4){0.f, 0.f, 0.f, 0.f};
;                 if (S0[hh]) sv[hh][it] = *(const f32x4*)(S0[hh] + (idx >> 5) * 128 + (idx & 31) * 4);
;                 else if (Sb) { const u32x2 v = *(const u32x2*)(Sb + (idx >> 5) * 128 + (idx & 31) * 4); sv[hh][it] = (f32x4){bf2f(v.x & 0xffffu), __uint_as_float(v.x & 0xffff0000u), bf2f(v.y & 0xffffu), __uint_as_float(v.y & 0xffff0000u)}; }
;             }
.LBB0_870:
	s_andn2_b64 vcc, exec, s[4:5]
	s_cbranch_vccnz .LBB0_881
	v_and_b32_e32 v52, 0xffffff80, v169
	v_ashrrev_i32_e32 v53, 31, v52
	v_lshl_add_u64 v[52:53], v[52:53], 1, v[32:33]
	global_load_dwordx2 v[66:67], v[52:53], off
	v_cndmask_b32_e64 v52, 0, 1, s[6:7]
	v_cmp_ne_u32_e64 s[26:27], 1, v52
	s_andn2_b64 vcc, exec, s[6:7]
	s_cbranch_vccz .LBB0_864
.LBB0_872:
.LBB0_873:
	s_andn2_b64 vcc, exec, s[4:5]
	s_cbranch_vccnz .LBB0_882
	v_lshlrev_b32_e32 v52, 2, v170
	v_and_b32_e32 v52, 0xffffff80, v52
	v_ashrrev_i32_e32 v53, 31, v52
	v_lshl_add_u64 v[52:53], v[52:53], 1, v[32:33]
	global_load_dwordx2 v[70:71], v[52:53], off
	s_and_b64 vcc, exec, s[26:27]
	s_cbranch_vccz .LBB0_866
.LBB0_875:
.LBB0_876:
	s_andn2_b64 vcc, exec, s[4:5]
	s_cbranch_vccnz .LBB0_883
	v_lshlrev_b32_e32 v52, 2, v171
	v_and_b32_e32 v52, 0xffffff80, v52
	v_ashrrev_i32_e32 v53, 31, v52
	v_lshl_add_u64 v[52:53], v[52:53], 1, v[32:33]
	global_load_dwordx2 v[74:75], v[52:53], off
	s_and_b64 vcc, exec, s[26:27]
	s_cbranch_vccz .LBB0_868
.LBB0_878:
.LBB0_879:
	s_andn2_b64 vcc, exec, s[4:5]
	s_cbranch_vccnz .LBB0_884
	v_lshlrev_b32_e32 v34, 2, v172
	v_and_b32_e32 v34, 0xffffff80, v34
	v_ashrrev_i32_e32 v35, 31, v34
	v_lshl_add_u64 v[32:33], v[34:35], 1, v[32:33]
	global_load_dwordx2 v[78:79], v[32:33], off
	s_branch .LBB0_885

; DI int crow(int reg, int h) { return (reg & 3) + 8 * (reg >> 2) + 4 * h; }
; template <bool FINAL>
; DI void gla_unit(KA a, int l, int item, LAS unsigned char* lds) {
;     ...
;     if (FINAL) {
; #pragma unroll
;         for (int q = 0; q < 4; ++q) gnv[q] = *(const f32x4*)(a->in[20] + l * DV + vdvc + 4 * q);
;     }
;     float s0v[2][16];
;     if (!FINAL && !u.prompt) {
; #pragma unroll
;         for (int hh = 0; hh < 2; ++hh)
; #pragma unroll
;             for (int i = 0; i < 16; ++i) s0v[hh][i] = __builtin_nontemporal_load(S0[hh] + (32 * (w >> 2) + crow(i, h)) * 128 + 32 * (w & 3) + r);
;     }
;     float bl[2][8];
;     {
;         float wg[2][16], bg[2];
; #pragma unroll
;         for (int hh = 0; hh < 2; ++hh) {
;             const float* wg2 = a->in[18] + (size_t)l * 16 * 256 + (2 * hp + hh) * 64 + dk;
; #pragma unroll
;             for (int e = 0; e < 16; ++e) wg[hh][e] = wg2[e * 256];
;             bg[hh] = a->in[19][l * 256 + (2 * hp + hh) * 64 + dk];
;         }
;         float run0 = 0.f, run1 = 0.f;
; #pragma unroll
;         for (int jj = 0; jj < 8; ++jj) {
;             const int t = 8 * tg + jj;
;             float ga = 0.f, gb = 0.f;
;             if (t < nvalid) {
;                 const u32x4* lp = (const u32x4*)(U + (size_t)(row0 + t) * UN + U_LR);
;                 float lr[16]; unpack8(lp[0], lr); unpack8(lp[1], lr + 8);
;                 float za = bg[0], zb = bg[1];
; #pragma unroll
;                 for (int e = 0; e < 16; ++e) { za += wg[0][e] * lr[e]; zb += wg[1][e] * lr[e]; }
.LBB0_885:
	s_load_dwordx4 s[4:7], s[2:3], 0x90
	s_nop 0
	s_load_dwordx2 s[2:3], s[2:3], 0xa0
	s_lshl_b64 s[26:27], s[60:61], 2
	v_lshlrev_b32_e32 v124, 2, v167
	v_lshlrev_b32_e32 v80, 2, v85
	v_mov_b32_e32 v81, v145
	s_waitcnt lgkmcnt(0)
	s_add_u32 s2, s2, s26
	s_addc_u32 s3, s3, s27
	global_load_dwordx4 v[32:35], v124, s[2:3] offset:48
	global_load_dwordx4 v[52:55], v124, s[2:3] offset:32
	global_load_dwordx4 v[56:59], v124, s[2:3] offset:16
	global_load_dwordx4 v[60:63], v124, s[2:3]
	v_readlane_b32 s2, v255, 1
	v_readlane_b32 s3, v255, 2
	s_lshl_b64 s[2:3], s[2:3], 2
	s_add_u32 s2, s4, s2
	s_addc_u32 s3, s5, s3
	v_readlane_b32 s0, v255, 3
	v_lshl_add_u64 v[80:81], s[2:3], 0, v[80:81]
	v_mov_b32_e32 v95, v145
	v_or_b32_e32 v110, s0, v85
	s_lshl_b32 s0, s54, 2
	v_lshl_add_u64 v[80:81], v[80:81], 0, s[0:1]
	s_movk_i32 s0, 0x1000
	v_add_co_u32_e32 v82, vcc, s0, v80
	s_movk_i32 s0, 0x2000
	s_nop 0
	v_addc_co_u32_e32 v83, vcc, 0, v81, vcc
	v_add_co_u32_e32 v86, vcc, s0, v80
	s_movk_i32 s0, 0x3000
	s_nop 0
	v_addc_co_u32_e32 v87, vcc, 0, v81, vcc
	v_add_co_u32_e32 v108, vcc, s0, v80
	v_or_b32_e32 v94, s54, v110
	s_nop 0
	v_addc_co_u32_e32 v109, vcc, 0, v81, vcc
	v_lshl_add_u64 v[94:95], v[94:95], 2, s[6:7]
	global_load_dword v176, v[80:81], off
	global_load_dword v175, v[80:81], off offset:1024
	global_load_dword v174, v[80:81], off offset:2048
	global_load_dword v173, v[80:81], off offset:3072
	global_load_dword v179, v[86:87], off offset:-4096
	global_load_dword v178, v[82:83], off offset:1024
	global_load_dword v99, v[82:83], off offset:2048
	global_load_dword v98, v[82:83], off offset:3072
	global_load_dword v97, v[86:87], off
	global_load_dword v96, v[86:87], off offset:1024
	global_load_dword v93, v[86:87], off offset:2048
	global_load_dword v92, v[86:87], off offset:3072
	global_load_dword v91, v[108:109], off
	global_load_dword v90, v[108:109], off offset:1024
	global_load_dword v89, v[108:109], off offset:2048
	global_load_dword v88, v[108:109], off offset:3072
	global_load_dword v177, v[94:95], off
	global_load_dword v182, v[80:81], off offset:256
	global_load_dword v181, v[80:81], off offset:1280
	global_load_dword v180, v[80:81], off offset:2304
	global_load_dword v185, v[80:81], off offset:3328
	global_load_dword v184, v[82:83], off offset:256
	global_load_dword v183, v[82:83], off offset:1280
	global_load_dword v107, v[82:83], off offset:2304
	global_load_dword v106, v[82:83], off offset:3328
	global_load_dword v105, v[86:87], off offset:256
	global_load_dword v104, v[86:87], off offset:1280
	global_load_dword v103, v[86:87], off offset:2304
	global_load_dword v102, v[86:87], off offset:3328
	global_load_dword v101, v[108:109], off offset:256
	global_load_dword v100, v[108:109], off offset:1280
	global_load_dword v95, v[108:109], off offset:2304
	global_load_dword v94, v[108:109], off offset:3328
	v_add_u32_e32 v80, s54, v110
	v_mov_b32_e32 v81, v145
	v_lshl_add_u64 v[80:81], v[80:81], 2, s[6:7]
	global_load_dword v186, v[80:81], off offset:256
	v_lshrrev_b32_e32 v192, 3, v85
	v_mul_u32_u24_e32 v192, 0x1600, v192
	v_and_b32_e32 v193, 7, v85
	v_lshl_add_u32 v192, v193, 2, v192
	s_add_i32 s72, s53, s46
	s_mul_hi_i32 s73, s72, 0x1600
	s_mulk_i32 s72, 0x1600
	s_add_u32 s72, s30, s72
	s_addc_u32 s73, s31, s73
	s_add_u32 s72, s72, 0x1400
	s_addc_u32 s73, s73, 0
	global_load_dword v193, v192, s[72:73]
	v_mov_b32_e32 v108, 0
	s_and_b64 vcc, exec, s[24:25]
	v_mov_b32_e32 v86, 0
	v_mov_b32_e32 v87, 0
	s_cbranch_vccnz .LBB0_887
	s_add_i32 s0, s53, s46
	s_mul_hi_i32 s3, s0, 0x1600
	s_mulk_i32 s0, 0x1600
	s_add_u32 s2, s30, s0
	s_addc_u32 s3, s31, s3
	s_add_u32 s4, s2, 0x1400
	s_addc_u32 s5, s3, 0
	s_mov_b32 s2, 0xbfb8aa3b
	s_mov_b32 s0, 0x800000
	s_mov_b32 s3, 0x3f317217
	s_mov_b32 s4, 0x7f800000
	s_waitcnt vmcnt(0)
	v_readlane_b32 s72, v193, 0
	v_readlane_b32 s73, v193, 1
	v_readlane_b32 s74, v193, 2
	v_readlane_b32 s75, v193, 3
	v_readlane_b32 s76, v193, 4
	v_readlane_b32 s77, v193, 5
	v_readlane_b32 s78, v193, 6
	v_readlane_b32 s79, v193, 7
	v_mov_b32_e32 v110, s72
	v_mov_b32_e32 v111, s73
	v_mov_b32_e32 v112, s74
	v_mov_b32_e32 v113, s75
	v_mov_b32_e32 v80, s76
	v_mov_b32_e32 v81, s77
	v_mov_b32_e32 v82, s78
	v_mov_b32_e32 v83, s79
	v_lshlrev_b32_e32 v86, 16, v110
	v_and_b32_e32 v87, 0xffff0000, v110
	v_fma_f32 v114, v176, v86, v177
	v_lshlrev_b32_e32 v109, 16, v111
	v_fma_f32 v115, v182, v86, v186
	v_fmac_f32_e32 v114, v175, v87
	v_and_b32_e32 v110, 0xffff0000, v111
	v_fmac_f32_e32 v115, v181, v87
	v_fmac_f32_e32 v114, v174, v109
	v_lshlrev_b32_e32 v111, 16, v112
	v_fmac_f32_e32 v115, v180, v109
	v_fmac_f32_e32 v114, v173, v110
	v_and_b32_e32 v112, 0xffff0000, v112
	v_fmac_f32_e32 v115, v185, v110
	v_fmac_f32_e32 v114, v179, v111
	v_and_b32_e32 v86, 0xffff0000, v113
	v_lshlrev_b32_e32 v87, 16, v113
	v_fmac_f32_e32 v115, v184, v111
	v_fmac_f32_e32 v114, v178, v112
	v_pk_mul_f32 v[110:111], v[106:107], v[86:87]
	v_pk_mul_f32 v[86:87], v[98:99], v[86:87]
	v_fmac_f32_e32 v115, v183, v112
	v_add_f32_e32 v87, v87, v114
	v_add_f32_e32 v109, v111, v115
	v_add_f32_e32 v112, v86, v87
	v_and_b32_e32 v86, 0xffff0000, v80
	v_lshlrev_b32_e32 v87, 16, v80
	v_add_f32_e32 v109, v110, v109
	v_pk_mul_f32 v[110:111], v[104:105], v[86:87]
	v_pk_mul_f32 v[86:87], v[96:97], v[86:87]
	v_add_f32_e32 v80, v111, v109
	v_add_f32_e32 v87, v87, v112
	v_add_f32_e32 v110, v110, v80
	v_and_b32_e32 v80, 0xffff0000, v81
	v_lshlrev_b32_e32 v81, 16, v81
	v_add_f32_e32 v109, v86, v87
	v_pk_mul_f32 v[86:87], v[102:103], v[80:81]
	v_pk_mul_f32 v[80:81], v[92:93], v[80:81]
	v_add_f32_e32 v87, v87, v110
	v_add_f32_e32 v81, v81, v109
	v_add_f32_e32 v109, v80, v81
; template <bool FINAL>
; DI void gla_unit(KA a, int l, int item, LAS unsigned char* lds) {
;     ...
;         for (int jj = 0; jj < 8; ++jj) {
;             const int t = 8 * tg + jj;
;             float ga = 0.f, gb = 0.f;
;             if (t < nvalid) {
;                 const u32x4* lp = (const u32x4*)(U + (size_t)(row0 + t) * UN + U_LR);
;                 float lr[16]; unpack8(lp[0], lr); unpack8(lp[1], lr + 8);
;                 float za = bg[0], zb = bg[1];
; #pragma unroll
;                 for (int e = 0; e < 16; ++e) { za += wg[0][e] * lr[e]; zb += wg[1][e] * lr[e]; }
;                 ga = (fminf(za, 0.f) - __logf(1.f + __expf(-fabsf(za)))) * (1.f / 16.f);
;                 gb = (fminf(zb, 0.f) - __logf(1.f + __expf(-fabsf(zb)))) * (1.f / 16.f);
;             }
;             run0 += ga; run1 += gb; bl[0][jj] = run0; bl[1][jj] = run1;
;         }
	v_and_b32_e32 v80, 0xffff0000, v82
	v_lshlrev_b32_e32 v81, 16, v82
	v_add_f32_e32 v110, v86, v87
	v_pk_mul_f32 v[86:87], v[100:101], v[80:81]
	v_pk_mul_f32 v[80:81], v[90:91], v[80:81]
	v_add_f32_e32 v82, v87, v110
	v_add_f32_e32 v81, v81, v109
	v_add_f32_e32 v87, v80, v81
	v_and_b32_e32 v80, 0xffff0000, v83
	v_lshlrev_b32_e32 v81, 16, v83
	v_add_f32_e32 v86, v86, v82
	v_pk_mul_f32 v[82:83], v[94:95], v[80:81]
	v_pk_mul_f32 v[80:81], v[88:89], v[80:81]
	v_add_f32_e32 v83, v83, v86
	v_add_f32_e32 v81, v81, v87
	v_add_f32_e32 v81, v80, v81
	v_min_f32_e32 v80, 0, v81
	v_mul_f32_e64 v81, |v81|, s2
	v_exp_f32_e32 v81, v81
	v_add_f32_e32 v83, v82, v83
	v_add_f32_e32 v81, 1.0, v81
	v_cmp_gt_f32_e32 vcc, s0, v81
	s_nop 1
	v_cndmask_b32_e64 v82, 0, 32, vcc
	v_ldexp_f32 v81, v81, v82
	v_log_f32_e32 v81, v81
	s_nop 0
	v_mul_f32_e32 v82, 0x3f317217, v81
	v_fma_f32 v82, v81, s3, -v82
	v_fmac_f32_e32 v82, 0x3377d1cf, v81
	v_fmac_f32_e32 v82, 0x3f317217, v81
	v_cmp_lt_f32_e64 s[24:25], |v81|, s4
	s_nop 1
	v_cndmask_b32_e64 v81, v81, v82, s[24:25]
	v_cndmask_b32_e32 v82, 0, v222, vcc
	v_sub_f32_e32 v82, v81, v82
	v_min_f32_e32 v81, 0, v83
	v_mul_f32_e64 v83, |v83|, s2
	v_exp_f32_e32 v83, v83
	s_nop 0
	v_add_f32_e32 v83, 1.0, v83
	v_cmp_gt_f32_e32 vcc, s0, v83
	s_mov_b32 s0, 0x3d800000
	s_nop 0
	v_cndmask_b32_e64 v86, 0, 32, vcc
	v_ldexp_f32 v83, v83, v86
	v_log_f32_e32 v83, v83
	s_nop 0
	v_mul_f32_e32 v86, 0x3f317217, v83
	v_fma_f32 v86, v83, s3, -v86
	v_fmac_f32_e32 v86, 0x3377d1cf, v83
	v_fmac_f32_e32 v86, 0x3f317217, v83
	v_cmp_lt_f32_e64 s[24:25], |v83|, s4
	s_nop 1
	v_cndmask_b32_e64 v83, v83, v86, s[24:25]
	v_cndmask_b32_e32 v86, 0, v222, vcc
	v_sub_f32_e32 v83, v83, v86
	v_pk_add_f32 v[80:81], v[80:81], v[82:83] neg_lo:[0,1] neg_hi:[0,1]
	s_nop 0
	v_pk_fma_f32 v[86:87], v[80:81], s[0:1], 0 op_sel_hi:[1,0,0]
.LBB0_887:
	s_and_b64 vcc, exec, s[22:23]
	v_mov_b32_e32 v109, 0
	s_cbranch_vccnz .LBB0_889
	s_add_i32 s0, s45, s46
	s_mul_hi_i32 s3, s0, 0x1600
	s_mulk_i32 s0, 0x1600
	s_add_u32 s2, s30, s0
	s_addc_u32 s3, s31, s3
	s_add_u32 s4, s2, 0x1400
	s_addc_u32 s5, s3, 0
	s_mov_b32 s2, 0xbfb8aa3b
	s_mov_b32 s0, 0x800000
	s_mov_b32 s3, 0x3f317217
	s_mov_b32 s4, 0x7f800000
	s_waitcnt vmcnt(0)
	v_readlane_b32 s72, v193, 8
	v_readlane_b32 s73, v193, 9
	v_readlane_b32 s74, v193, 10
	v_readlane_b32 s75, v193, 11
	v_readlane_b32 s76, v193, 12
	v_readlane_b32 s77, v193, 13
	v_readlane_b32 s78, v193, 14
	v_readlane_b32 s79, v193, 15
	v_mov_b32_e32 v108, s72
	v_mov_b32_e32 v109, s73
	v_mov_b32_e32 v110, s74
	v_mov_b32_e32 v111, s75
	v_mov_b32_e32 v80, s76
	v_mov_b32_e32 v81, s77
	v_mov_b32_e32 v82, s78
	v_mov_b32_e32 v83, s79
	v_lshlrev_b32_e32 v112, 16, v108
	v_and_b32_e32 v108, 0xffff0000, v108
	v_fma_f32 v115, v176, v112, v177
	v_fma_f32 v112, v182, v112, v186
	v_lshlrev_b32_e32 v113, 16, v109
	v_fmac_f32_e32 v115, v175, v108
	v_fmac_f32_e32 v112, v181, v108
	v_and_b32_e32 v109, 0xffff0000, v109
	v_fmac_f32_e32 v115, v174, v113
	v_fmac_f32_e32 v112, v180, v113
	v_lshlrev_b32_e32 v114, 16, v110
	v_fmac_f32_e32 v115, v173, v109
	v_fmac_f32_e32 v112, v185, v109
	v_and_b32_e32 v110, 0xffff0000, v110
	v_fmac_f32_e32 v115, v179, v114
	v_fmac_f32_e32 v112, v184, v114
	v_and_b32_e32 v108, 0xffff0000, v111
	v_lshlrev_b32_e32 v109, 16, v111
	v_fmac_f32_e32 v115, v178, v110
	v_fmac_f32_e32 v112, v183, v110
	v_pk_mul_f32 v[110:111], v[98:99], v[108:109]
	v_pk_mul_f32 v[108:109], v[106:107], v[108:109]
	v_add_f32_e32 v111, v111, v115
	v_add_f32_e32 v109, v109, v112
	v_add_f32_e32 v112, v108, v109
	v_and_b32_e32 v108, 0xffff0000, v80
	v_lshlrev_b32_e32 v109, 16, v80
	v_add_f32_e32 v113, v110, v111
	v_pk_mul_f32 v[110:111], v[96:97], v[108:109]
	v_pk_mul_f32 v[108:109], v[104:105], v[108:109]
	v_add_f32_e32 v80, v111, v113
	v_add_f32_e32 v110, v110, v80
	v_add_f32_e32 v80, v109, v112
	v_add_f32_e32 v111, v108, v80
	v_and_b32_e32 v80, 0xffff0000, v81
	v_lshlrev_b32_e32 v81, 16, v81
	v_pk_mul_f32 v[108:109], v[92:93], v[80:81]
	v_pk_mul_f32 v[80:81], v[102:103], v[80:81]
	v_add_f32_e32 v109, v109, v110
	v_add_f32_e32 v81, v81, v111
	v_add_f32_e32 v111, v80, v81
	v_and_b32_e32 v80, 0xffff0000, v82
	v_lshlrev_b32_e32 v81, 16, v82
	v_add_f32_e32 v110, v108, v109
	v_pk_mul_f32 v[108:109], v[90:91], v[80:81]
	v_pk_mul_f32 v[80:81], v[100:101], v[80:81]
	v_add_f32_e32 v82, v109, v110
	v_add_f32_e32 v81, v81, v111
	v_add_f32_e32 v109, v80, v81
	v_and_b32_e32 v80, 0xffff0000, v83
	v_lshlrev_b32_e32 v81, 16, v83
	v_add_f32_e32 v108, v108, v82
	v_pk_mul_f32 v[82:83], v[88:89], v[80:81]
	v_pk_mul_f32 v[80:81], v[94:95], v[80:81]
	v_add_f32_e32 v83, v83, v108
	v_add_f32_e32 v82, v82, v83
	v_add_f32_e32 v81, v81, v109
	v_add_f32_e32 v108, v80, v81
	v_mul_f32_e64 v80, |v82|, s2
	v_exp_f32_e32 v80, v80
	v_min_f32_e32 v81, 0, v82
	v_add_f32_e32 v80, 1.0, v80
	v_cmp_gt_f32_e32 vcc, s0, v80
	s_nop 1
	v_cndmask_b32_e64 v82, 0, 32, vcc
	v_ldexp_f32 v80, v80, v82
	v_log_f32_e32 v80, v80
	s_nop 0
	v_mul_f32_e32 v82, 0x3f317217, v80
	v_fma_f32 v82, v80, s3, -v82
	v_fmac_f32_e32 v82, 0x3377d1cf, v80
	v_fmac_f32_e32 v82, 0x3f317217, v80
	v_cmp_lt_f32_e64 s[22:23], |v80|, s4
	s_nop 1
	v_cndmask_b32_e64 v80, v80, v82, s[22:23]
	v_cndmask_b32_e32 v82, 0, v222, vcc
	v_sub_f32_e32 v83, v80, v82
	v_mul_f32_e64 v82, |v108|, s2
	v_exp_f32_e32 v82, v82
	v_min_f32_e32 v80, 0, v108
	v_add_f32_e32 v82, 1.0, v82
	v_cmp_gt_f32_e32 vcc, s0, v82
	s_mov_b32 s0, 0x3d800000
	s_nop 0
	v_cndmask_b32_e64 v108, 0, 32, vcc
	v_ldexp_f32 v82, v82, v108
	v_log_f32_e32 v82, v82
	s_nop 0
	v_mul_f32_e32 v108, 0x3f317217, v82
	v_fma_f32 v108, v82, s3, -v108
	v_fmac_f32_e32 v108, 0x3377d1cf, v82
	v_fmac_f32_e32 v108, 0x3f317217, v82
	v_cmp_lt_f32_e64 s[22:23], |v82|, s4
	s_nop 1
	v_cndmask_b32_e64 v82, v82, v108, s[22:23]
	v_cndmask_b32_e32 v108, 0, v222, vcc
	v_sub_f32_e32 v82, v82, v108
	v_pk_add_f32 v[80:81], v[80:81], v[82:83] neg_lo:[0,1] neg_hi:[0,1]
	s_nop 0
	v_pk_mul_f32 v[108:109], v[80:81], s[0:1] op_sel_hi:[1,0]
; template <bool FINAL>
; DI void gla_unit(KA a, int l, int item, LAS unsigned char* lds) {
;     ...
;         for (int jj = 0; jj < 8; ++jj) {
;             const int t = 8 * tg + jj;
;             float ga = 0.f, gb = 0.f;
;             if (t < nvalid) {
;                 const u32x4* lp = (const u32x4*)(U + (size_t)(row0 + t) * UN + U_LR);
;                 float lr[16]; unpack8(lp[0], lr); unpack8(lp[1], lr + 8);
;                 float za = bg[0], zb = bg[1];
; #pragma unroll
;                 for (int e = 0; e < 16; ++e) { za += wg[0][e] * lr[e]; zb += wg[1][e] * lr[e]; }
;                 ga = (fminf(za, 0.f) - __logf(1.f + __expf(-fabsf(za)))) * (1.f / 16.f);
;                 gb = (fminf(zb, 0.f) - __logf(1.f + __expf(-fabsf(zb)))) * (1.f / 16.f);
;             }
;             run0 += ga; run1 += gb; bl[0][jj] = run0; bl[1][jj] = run1;
;         }
.LBB0_889:
	v_mov_b32_e32 v110, 0
	s_and_b64 vcc, exec, s[20:21]
	v_mov_b32_e32 v112, 0
	v_mov_b32_e32 v113, 0
	s_cbranch_vccnz .LBB0_891
	s_add_i32 s0, s52, s46
	s_mul_hi_i32 s3, s0, 0x1600
	s_mulk_i32 s0, 0x1600
	s_add_u32 s2, s30, s0
	s_addc_u32 s3, s31, s3
	s_add_u32 s4, s2, 0x1400
	s_addc_u32 s5, s3, 0
	s_mov_b32 s2, 0xbfb8aa3b
	s_mov_b32 s0, 0x800000
	s_mov_b32 s3, 0x3f317217
	s_mov_b32 s4, 0x7f800000
	s_waitcnt vmcnt(0)
	v_readlane_b32 s72, v193, 16
	v_readlane_b32 s73, v193, 17
	v_readlane_b32 s74, v193, 18
	v_readlane_b32 s75, v193, 19
	v_readlane_b32 s76, v193, 20
	v_readlane_b32 s77, v193, 21
	v_readlane_b32 s78, v193, 22
	v_readlane_b32 s79, v193, 23
	v_mov_b32_e32 v112, s72
	v_mov_b32_e32 v113, s73
	v_mov_b32_e32 v114, s74
	v_mov_b32_e32 v115, s75
	v_mov_b32_e32 v80, s76
	v_mov_b32_e32 v81, s77
	v_mov_b32_e32 v82, s78
	v_mov_b32_e32 v83, s79
	v_lshlrev_b32_e32 v111, 16, v112
	v_and_b32_e32 v112, 0xffff0000, v112
	v_fma_f32 v118, v176, v111, v177
	v_fma_f32 v111, v182, v111, v186
	v_lshlrev_b32_e32 v116, 16, v113
	v_fmac_f32_e32 v118, v175, v112
	v_fmac_f32_e32 v111, v181, v112
	v_and_b32_e32 v113, 0xffff0000, v113
	v_fmac_f32_e32 v118, v174, v116
	v_fmac_f32_e32 v111, v180, v116
	v_lshlrev_b32_e32 v117, 16, v114
	v_fmac_f32_e32 v118, v173, v113
	v_fmac_f32_e32 v111, v185, v113
	v_and_b32_e32 v114, 0xffff0000, v114
	v_fmac_f32_e32 v118, v179, v117
	v_fmac_f32_e32 v111, v184, v117
	v_and_b32_e32 v112, 0xffff0000, v115
	v_lshlrev_b32_e32 v113, 16, v115
	v_fmac_f32_e32 v118, v178, v114
	v_fmac_f32_e32 v111, v183, v114
	v_pk_mul_f32 v[114:115], v[98:99], v[112:113]
	v_pk_mul_f32 v[112:113], v[106:107], v[112:113]
	v_add_f32_e32 v115, v115, v118
	v_add_f32_e32 v111, v113, v111
	v_add_f32_e32 v111, v112, v111
	v_and_b32_e32 v112, 0xffff0000, v80
	v_lshlrev_b32_e32 v113, 16, v80
	v_add_f32_e32 v116, v114, v115
	v_pk_mul_f32 v[114:115], v[96:97], v[112:113]
	v_pk_mul_f32 v[112:113], v[104:105], v[112:113]
	v_add_f32_e32 v80, v115, v116
	v_add_f32_e32 v114, v114, v80
	v_add_f32_e32 v80, v113, v111
	v_add_f32_e32 v111, v112, v80
	v_and_b32_e32 v80, 0xffff0000, v81
	v_lshlrev_b32_e32 v81, 16, v81
	v_pk_mul_f32 v[112:113], v[92:93], v[80:81]
	v_pk_mul_f32 v[80:81], v[102:103], v[80:81]
	v_add_f32_e32 v113, v113, v114
	v_add_f32_e32 v81, v81, v111
	v_add_f32_e32 v111, v80, v81
	v_and_b32_e32 v80, 0xffff0000, v82
	v_lshlrev_b32_e32 v81, 16, v82
	v_add_f32_e32 v114, v112, v113
	v_pk_mul_f32 v[112:113], v[90:91], v[80:81]
	v_pk_mul_f32 v[80:81], v[100:101], v[80:81]
	v_add_f32_e32 v82, v113, v114
	v_add_f32_e32 v81, v81, v111
	v_add_f32_e32 v111, v80, v81
	v_and_b32_e32 v80, 0xffff0000, v83
	v_lshlrev_b32_e32 v81, 16, v83
	v_add_f32_e32 v112, v112, v82
	v_pk_mul_f32 v[82:83], v[88:89], v[80:81]
	v_pk_mul_f32 v[80:81], v[94:95], v[80:81]
	v_add_f32_e32 v83, v83, v112
	v_add_f32_e32 v82, v82, v83
	v_add_f32_e32 v81, v81, v111
	v_add_f32_e32 v111, v80, v81
	v_mul_f32_e64 v80, |v82|, s2
	v_exp_f32_e32 v80, v80
	v_min_f32_e32 v81, 0, v82
	v_add_f32_e32 v80, 1.0, v80
	v_cmp_gt_f32_e32 vcc, s0, v80
	s_nop 1
	v_cndmask_b32_e64 v82, 0, 32, vcc
	v_ldexp_f32 v80, v80, v82
	v_log_f32_e32 v80, v80
	s_nop 0
	v_mul_f32_e32 v82, 0x3f317217, v80
	v_fma_f32 v82, v80, s3, -v82
	v_fmac_f32_e32 v82, 0x3377d1cf, v80
	v_fmac_f32_e32 v82, 0x3f317217, v80
	v_cmp_lt_f32_e64 s[20:21], |v80|, s4
	s_nop 1
	v_cndmask_b32_e64 v80, v80, v82, s[20:21]
	v_cndmask_b32_e32 v82, 0, v222, vcc
	v_sub_f32_e32 v83, v80, v82
	v_mul_f32_e64 v82, |v111|, s2
	v_exp_f32_e32 v82, v82
	v_min_f32_e32 v80, 0, v111
	v_add_f32_e32 v82, 1.0, v82
	v_cmp_gt_f32_e32 vcc, s0, v82
	s_mov_b32 s0, 0x3d800000
	s_nop 0
	v_cndmask_b32_e64 v111, 0, 32, vcc
	v_ldexp_f32 v82, v82, v111
	v_log_f32_e32 v82, v82
	s_nop 0
	v_mul_f32_e32 v111, 0x3f317217, v82
	v_fma_f32 v111, v82, s3, -v111
	v_fmac_f32_e32 v111, 0x3377d1cf, v82
	v_fmac_f32_e32 v111, 0x3f317217, v82
	v_cmp_lt_f32_e64 s[20:21], |v82|, s4
	s_nop 1
	v_cndmask_b32_e64 v82, v82, v111, s[20:21]
	v_cndmask_b32_e32 v111, 0, v222, vcc
	v_sub_f32_e32 v82, v82, v111
	v_pk_add_f32 v[80:81], v[80:81], v[82:83] neg_lo:[0,1] neg_hi:[0,1]
	s_nop 0
	v_pk_mul_f32 v[112:113], v[80:81], s[0:1] op_sel_hi:[1,0]
.LBB0_891:
	s_and_b64 vcc, exec, s[18:19]
	v_mov_b32_e32 v111, 0
	s_cbranch_vccnz .LBB0_893
; template <bool FINAL>
; DI void gla_unit(KA a, int l, int item, LAS unsigned char* lds) {
;     ...
;         for (int jj = 0; jj < 8; ++jj) {
;             const int t = 8 * tg + jj;
;             float ga = 0.f, gb = 0.f;
;             if (t < nvalid) {
;                 const u32x4* lp = (const u32x4*)(U + (size_t)(row0 + t) * UN + U_LR);
;                 float lr[16]; unpack8(lp[0], lr); unpack8(lp[1], lr + 8);
;                 float za = bg[0], zb = bg[1];
; #pragma unroll
;                 for (int e = 0; e < 16; ++e) { za += wg[0][e] * lr[e]; zb += wg[1][e] * lr[e]; }
;                 ga = (fminf(za, 0.f) - __logf(1.f + __expf(-fabsf(za)))) * (1.f / 16.f);
;                 gb = (fminf(zb, 0.f) - __logf(1.f + __expf(-fabsf(zb)))) * (1.f / 16.f);
;             }
;             run0 += ga; run1 += gb; bl[0][jj] = run0; bl[1][jj] = run1;
;         }
	s_add_i32 s0, s51, s46
	s_mul_hi_i32 s3, s0, 0x1600
	s_mulk_i32 s0, 0x1600
	s_add_u32 s2, s30, s0
	s_addc_u32 s3, s31, s3
	s_add_u32 s4, s2, 0x1400
	s_addc_u32 s5, s3, 0
	s_mov_b32 s2, 0xbfb8aa3b
	s_mov_b32 s0, 0x800000
	s_mov_b32 s3, 0x3f317217
	s_mov_b32 s4, 0x7f800000
	s_waitcnt vmcnt(0)
	v_readlane_b32 s72, v193, 24
	v_readlane_b32 s73, v193, 25
	v_readlane_b32 s74, v193, 26
	v_readlane_b32 s75, v193, 27
	v_readlane_b32 s76, v193, 28
	v_readlane_b32 s77, v193, 29
	v_readlane_b32 s78, v193, 30
	v_readlane_b32 s79, v193, 31
	v_mov_b32_e32 v114, s72
	v_mov_b32_e32 v115, s73
	v_mov_b32_e32 v116, s74
	v_mov_b32_e32 v117, s75
	v_mov_b32_e32 v80, s76
	v_mov_b32_e32 v81, s77
	v_mov_b32_e32 v82, s78
	v_mov_b32_e32 v83, s79
	v_lshlrev_b32_e32 v110, 16, v114
	v_and_b32_e32 v111, 0xffff0000, v114
	v_fma_f32 v120, v182, v110, v186
	v_lshlrev_b32_e32 v114, 16, v115
	v_fma_f32 v119, v176, v110, v177
	v_fmac_f32_e32 v120, v181, v111
	v_and_b32_e32 v115, 0xffff0000, v115
	v_fmac_f32_e32 v119, v175, v111
	v_fmac_f32_e32 v120, v180, v114
	v_lshlrev_b32_e32 v118, 16, v116
	v_fmac_f32_e32 v119, v174, v114
	v_fmac_f32_e32 v120, v185, v115
	v_and_b32_e32 v116, 0xffff0000, v116
	v_fmac_f32_e32 v119, v173, v115
	v_fmac_f32_e32 v120, v184, v118
	v_and_b32_e32 v110, 0xffff0000, v117
	v_lshlrev_b32_e32 v111, 16, v117
	v_fmac_f32_e32 v119, v179, v118
	v_fmac_f32_e32 v120, v183, v116
	v_pk_mul_f32 v[114:115], v[98:99], v[110:111]
	v_pk_mul_f32 v[110:111], v[106:107], v[110:111]
	v_fmac_f32_e32 v119, v178, v116
	v_add_f32_e32 v111, v111, v120
	v_add_f32_e32 v115, v115, v119
	v_add_f32_e32 v117, v110, v111
	v_and_b32_e32 v110, 0xffff0000, v80
	v_lshlrev_b32_e32 v111, 16, v80
	v_add_f32_e32 v116, v114, v115
	v_pk_mul_f32 v[114:115], v[96:97], v[110:111]
	v_pk_mul_f32 v[110:111], v[104:105], v[110:111]
	v_add_f32_e32 v80, v115, v116
	v_add_f32_e32 v114, v114, v80
	v_add_f32_e32 v80, v111, v117
	v_add_f32_e32 v115, v110, v80
	v_and_b32_e32 v80, 0xffff0000, v81
	v_lshlrev_b32_e32 v81, 16, v81
	v_pk_mul_f32 v[110:111], v[92:93], v[80:81]
	v_pk_mul_f32 v[80:81], v[102:103], v[80:81]
	v_add_f32_e32 v111, v111, v114
	v_add_f32_e32 v81, v81, v115
	v_add_f32_e32 v115, v80, v81
	v_and_b32_e32 v80, 0xffff0000, v82
	v_lshlrev_b32_e32 v81, 16, v82
	v_add_f32_e32 v114, v110, v111
	v_pk_mul_f32 v[110:111], v[90:91], v[80:81]
	v_pk_mul_f32 v[80:81], v[100:101], v[80:81]
	v_add_f32_e32 v82, v111, v114
	v_add_f32_e32 v81, v81, v115
	v_add_f32_e32 v111, v80, v81
	v_and_b32_e32 v80, 0xffff0000, v83
	v_lshlrev_b32_e32 v81, 16, v83
	v_add_f32_e32 v110, v110, v82
	v_pk_mul_f32 v[82:83], v[88:89], v[80:81]
	v_pk_mul_f32 v[80:81], v[94:95], v[80:81]
	v_add_f32_e32 v83, v83, v110
	v_add_f32_e32 v82, v82, v83
	v_add_f32_e32 v81, v81, v111
	v_add_f32_e32 v110, v80, v81
	v_mul_f32_e64 v80, |v82|, s2
	v_exp_f32_e32 v80, v80
	v_min_f32_e32 v81, 0, v82
	v_add_f32_e32 v80, 1.0, v80
	v_cmp_gt_f32_e32 vcc, s0, v80
	s_nop 1
	v_cndmask_b32_e64 v82, 0, 32, vcc
	v_ldexp_f32 v80, v80, v82
	v_log_f32_e32 v80, v80
	s_nop 0
	v_mul_f32_e32 v82, 0x3f317217, v80
	v_fma_f32 v82, v80, s3, -v82
	v_fmac_f32_e32 v82, 0x3377d1cf, v80
	v_fmac_f32_e32 v82, 0x3f317217, v80
	v_cmp_lt_f32_e64 s[18:19], |v80|, s4
	s_nop 1
	v_cndmask_b32_e64 v80, v80, v82, s[18:19]
	v_cndmask_b32_e32 v82, 0, v222, vcc
	v_sub_f32_e32 v83, v80, v82
	v_mul_f32_e64 v82, |v110|, s2
	v_exp_f32_e32 v82, v82
	v_min_f32_e32 v80, 0, v110
	v_add_f32_e32 v82, 1.0, v82
	v_cmp_gt_f32_e32 vcc, s0, v82
	s_mov_b32 s0, 0x3d800000
	s_nop 0
	v_cndmask_b32_e64 v110, 0, 32, vcc
	v_ldexp_f32 v82, v82, v110
	v_log_f32_e32 v82, v82
	s_nop 0
	v_mul_f32_e32 v110, 0x3f317217, v82
	v_fma_f32 v110, v82, s3, -v110
	v_fmac_f32_e32 v110, 0x3377d1cf, v82
	v_fmac_f32_e32 v110, 0x3f317217, v82
	v_cmp_lt_f32_e64 s[18:19], |v82|, s4
	s_nop 1
	v_cndmask_b32_e64 v82, v82, v110, s[18:19]
	v_cndmask_b32_e32 v110, 0, v222, vcc
	v_sub_f32_e32 v82, v82, v110
	v_pk_add_f32 v[80:81], v[80:81], v[82:83] neg_lo:[0,1] neg_hi:[0,1]
	s_nop 0
	v_pk_mul_f32 v[110:111], v[80:81], s[0:1] op_sel_hi:[1,0]
.LBB0_893:
	v_mov_b32_e32 v114, 0
	s_and_b64 vcc, exec, s[16:17]
	v_mov_b32_e32 v116, 0
	v_mov_b32_e32 v117, 0
	s_cbranch_vccnz .LBB0_895
	s_add_i32 s0, s50, s46
	s_mul_hi_i32 s3, s0, 0x1600
	s_mulk_i32 s0, 0x1600
	s_add_u32 s2, s30, s0
	s_addc_u32 s3, s31, s3
	s_add_u32 s4, s2, 0x1400
	s_addc_u32 s5, s3, 0
	s_mov_b32 s2, 0xbfb8aa3b
	s_mov_b32 s0, 0x800000
	s_mov_b32 s3, 0x3f317217
	s_mov_b32 s4, 0x7f800000
	s_waitcnt vmcnt(0)
; template <bool FINAL>
; DI void gla_unit(KA a, int l, int item, LAS unsigned char* lds) {
;     ...
;         for (int jj = 0; jj < 8; ++jj) {
;             const int t = 8 * tg + jj;
;             float ga = 0.f, gb = 0.f;
;             if (t < nvalid) {
;                 const u32x4* lp = (const u32x4*)(U + (size_t)(row0 + t) * UN + U_LR);
;                 float lr[16]; unpack8(lp[0], lr); unpack8(lp[1], lr + 8);
;                 float za = bg[0], zb = bg[1];
; #pragma unroll
;                 for (int e = 0; e < 16; ++e) { za += wg[0][e] * lr[e]; zb += wg[1][e] * lr[e]; }
;                 ga = (fminf(za, 0.f) - __logf(1.f + __expf(-fabsf(za)))) * (1.f / 16.f);
;                 gb = (fminf(zb, 0.f) - __logf(1.f + __expf(-fabsf(zb)))) * (1.f / 16.f);
;             }
;             run0 += ga; run1 += gb; bl[0][jj] = run0; bl[1][jj] = run1;
;         }
	v_readlane_b32 s72, v193, 32
	v_readlane_b32 s73, v193, 33
	v_readlane_b32 s74, v193, 34
	v_readlane_b32 s75, v193, 35
	v_readlane_b32 s76, v193, 36
	v_readlane_b32 s77, v193, 37
	v_readlane_b32 s78, v193, 38
	v_readlane_b32 s79, v193, 39
	v_mov_b32_e32 v116, s72
	v_mov_b32_e32 v117, s73
	v_mov_b32_e32 v118, s74
	v_mov_b32_e32 v119, s75
	v_mov_b32_e32 v80, s76
	v_mov_b32_e32 v81, s77
	v_mov_b32_e32 v82, s78
	v_mov_b32_e32 v83, s79
	v_lshlrev_b32_e32 v115, 16, v116
	v_and_b32_e32 v116, 0xffff0000, v116
	v_fma_f32 v187, v176, v115, v177
	v_fma_f32 v115, v182, v115, v186
	v_lshlrev_b32_e32 v120, 16, v117
	v_fmac_f32_e32 v187, v175, v116
	v_fmac_f32_e32 v115, v181, v116
	v_and_b32_e32 v117, 0xffff0000, v117
	v_fmac_f32_e32 v187, v174, v120
	v_fmac_f32_e32 v115, v180, v120
	v_lshlrev_b32_e32 v121, 16, v118
	v_fmac_f32_e32 v187, v173, v117
	v_fmac_f32_e32 v115, v185, v117
	v_and_b32_e32 v118, 0xffff0000, v118
	v_fmac_f32_e32 v187, v179, v121
	v_fmac_f32_e32 v115, v184, v121
	v_and_b32_e32 v116, 0xffff0000, v119
	v_lshlrev_b32_e32 v117, 16, v119
	v_fmac_f32_e32 v187, v178, v118
	v_fmac_f32_e32 v115, v183, v118
	v_pk_mul_f32 v[118:119], v[98:99], v[116:117]
	v_pk_mul_f32 v[116:117], v[106:107], v[116:117]
	v_add_f32_e32 v119, v119, v187
	v_add_f32_e32 v115, v117, v115
	v_add_f32_e32 v115, v116, v115
	v_and_b32_e32 v116, 0xffff0000, v80
	v_lshlrev_b32_e32 v117, 16, v80
	v_add_f32_e32 v120, v118, v119
	v_pk_mul_f32 v[118:119], v[96:97], v[116:117]
	v_pk_mul_f32 v[116:117], v[104:105], v[116:117]
	v_add_f32_e32 v80, v119, v120
	v_add_f32_e32 v118, v118, v80
	v_add_f32_e32 v80, v117, v115
	v_add_f32_e32 v115, v116, v80
	v_and_b32_e32 v80, 0xffff0000, v81
	v_lshlrev_b32_e32 v81, 16, v81
	v_pk_mul_f32 v[116:117], v[92:93], v[80:81]
	v_pk_mul_f32 v[80:81], v[102:103], v[80:81]
	v_add_f32_e32 v117, v117, v118
	v_add_f32_e32 v81, v81, v115
	v_add_f32_e32 v115, v80, v81
	v_and_b32_e32 v80, 0xffff0000, v82
	v_lshlrev_b32_e32 v81, 16, v82
	v_add_f32_e32 v118, v116, v117
	v_pk_mul_f32 v[116:117], v[90:91], v[80:81]
	v_pk_mul_f32 v[80:81], v[100:101], v[80:81]
	v_add_f32_e32 v82, v117, v118
	v_add_f32_e32 v81, v81, v115
	v_add_f32_e32 v115, v80, v81
	v_and_b32_e32 v80, 0xffff0000, v83
	v_lshlrev_b32_e32 v81, 16, v83
	v_add_f32_e32 v116, v116, v82
	v_pk_mul_f32 v[82:83], v[88:89], v[80:81]
	v_pk_mul_f32 v[80:81], v[94:95], v[80:81]
	v_add_f32_e32 v83, v83, v116
	v_add_f32_e32 v82, v82, v83
	v_add_f32_e32 v81, v81, v115
	v_add_f32_e32 v115, v80, v81
	v_mul_f32_e64 v80, |v82|, s2
	v_exp_f32_e32 v80, v80
	v_min_f32_e32 v81, 0, v82
	v_add_f32_e32 v80, 1.0, v80
	v_cmp_gt_f32_e32 vcc, s0, v80
	s_nop 1
	v_cndmask_b32_e64 v82, 0, 32, vcc
	v_ldexp_f32 v80, v80, v82
	v_log_f32_e32 v80, v80
	s_nop 0
	v_mul_f32_e32 v82, 0x3f317217, v80
	v_fma_f32 v82, v80, s3, -v82
	v_fmac_f32_e32 v82, 0x3377d1cf, v80
	v_fmac_f32_e32 v82, 0x3f317217, v80
	v_cmp_lt_f32_e64 s[16:17], |v80|, s4
	s_nop 1
	v_cndmask_b32_e64 v80, v80, v82, s[16:17]
	v_cndmask_b32_e32 v82, 0, v222, vcc
	v_sub_f32_e32 v83, v80, v82
	v_mul_f32_e64 v82, |v115|, s2
	v_exp_f32_e32 v82, v82
	v_min_f32_e32 v80, 0, v115
	v_add_f32_e32 v82, 1.0, v82
	v_cmp_gt_f32_e32 vcc, s0, v82
	s_mov_b32 s0, 0x3d800000
	s_nop 0
	v_cndmask_b32_e64 v115, 0, 32, vcc
	v_ldexp_f32 v82, v82, v115
	v_log_f32_e32 v82, v82
	s_nop 0
	v_mul_f32_e32 v115, 0x3f317217, v82
	v_fma_f32 v115, v82, s3, -v115
	v_fmac_f32_e32 v115, 0x3377d1cf, v82
	v_fmac_f32_e32 v115, 0x3f317217, v82
	v_cmp_lt_f32_e64 s[16:17], |v82|, s4
	s_nop 1
	v_cndmask_b32_e64 v82, v82, v115, s[16:17]
	v_cndmask_b32_e32 v115, 0, v222, vcc
	v_sub_f32_e32 v82, v82, v115
	v_pk_add_f32 v[80:81], v[80:81], v[82:83] neg_lo:[0,1] neg_hi:[0,1]
	s_nop 0
	v_pk_mul_f32 v[116:117], v[80:81], s[0:1] op_sel_hi:[1,0]
.LBB0_895:
	s_and_b64 vcc, exec, s[14:15]
	v_mov_b32_e32 v115, 0
	s_cbranch_vccnz .LBB0_897
	s_add_i32 s0, s49, s46
	s_mul_hi_i32 s3, s0, 0x1600
	s_mulk_i32 s0, 0x1600
	s_add_u32 s2, s30, s0
	s_addc_u32 s3, s31, s3
	s_add_u32 s4, s2, 0x1400
	s_addc_u32 s5, s3, 0
	s_mov_b32 s2, 0xbfb8aa3b
	s_mov_b32 s0, 0x800000
	s_mov_b32 s3, 0x3f317217
	s_mov_b32 s4, 0x7f800000
	s_waitcnt vmcnt(0)
	v_readlane_b32 s72, v193, 40
	v_readlane_b32 s73, v193, 41
	v_readlane_b32 s74, v193, 42
	v_readlane_b32 s75, v193, 43
	v_readlane_b32 s76, v193, 44
	v_readlane_b32 s77, v193, 45
	v_readlane_b32 s78, v193, 46
	v_readlane_b32 s79, v193, 47
	v_mov_b32_e32 v118, s72
	v_mov_b32_e32 v119, s73
	v_mov_b32_e32 v120, s74
	v_mov_b32_e32 v121, s75
	v_mov_b32_e32 v80, s76
	v_mov_b32_e32 v81, s77
	v_mov_b32_e32 v82, s78
	v_mov_b32_e32 v83, s79
	v_lshlrev_b32_e32 v114, 16, v118
	v_and_b32_e32 v115, 0xffff0000, v118
	v_fma_f32 v189, v182, v114, v186
	v_lshlrev_b32_e32 v118, 16, v119
	v_fma_f32 v188, v176, v114, v177
	v_fmac_f32_e32 v189, v181, v115
	v_and_b32_e32 v119, 0xffff0000, v119
	v_fmac_f32_e32 v188, v175, v115
	v_fmac_f32_e32 v189, v180, v118
	v_lshlrev_b32_e32 v187, 16, v120
	v_fmac_f32_e32 v188, v174, v118
	v_fmac_f32_e32 v189, v185, v119
	v_and_b32_e32 v120, 0xffff0000, v120
	v_fmac_f32_e32 v188, v173, v119
	v_fmac_f32_e32 v189, v184, v187
	v_and_b32_e32 v114, 0xffff0000, v121
	v_lshlrev_b32_e32 v115, 16, v121
	v_fmac_f32_e32 v188, v179, v187
	v_fmac_f32_e32 v189, v183, v120
	v_pk_mul_f32 v[118:119], v[98:99], v[114:115]
	v_pk_mul_f32 v[114:115], v[106:107], v[114:115]
	v_fmac_f32_e32 v188, v178, v120
	v_add_f32_e32 v115, v115, v189
	v_add_f32_e32 v119, v119, v188
	v_add_f32_e32 v121, v114, v115
	v_and_b32_e32 v114, 0xffff0000, v80
	v_lshlrev_b32_e32 v115, 16, v80
	v_add_f32_e32 v120, v118, v119
	v_pk_mul_f32 v[118:119], v[96:97], v[114:115]
	v_pk_mul_f32 v[114:115], v[104:105], v[114:115]
; template <bool FINAL>
; DI void gla_unit(KA a, int l, int item, LAS unsigned char* lds) {
;     ...
;         for (int jj = 0; jj < 8; ++jj) {
;             const int t = 8 * tg + jj;
;             float ga = 0.f, gb = 0.f;
;             if (t < nvalid) {
;                 const u32x4* lp = (const u32x4*)(U + (size_t)(row0 + t) * UN + U_LR);
;                 float lr[16]; unpack8(lp[0], lr); unpack8(lp[1], lr + 8);
;                 float za = bg[0], zb = bg[1];
; #pragma unroll
;                 for (int e = 0; e < 16; ++e) { za += wg[0][e] * lr[e]; zb += wg[1][e] * lr[e]; }
;                 ga = (fminf(za, 0.f) - __logf(1.f + __expf(-fabsf(za)))) * (1.f / 16.f);
;                 gb = (fminf(zb, 0.f) - __logf(1.f + __expf(-fabsf(zb)))) * (1.f / 16.f);
;             }
;             run0 += ga; run1 += gb; bl[0][jj] = run0; bl[1][jj] = run1;
;         }
	v_add_f32_e32 v80, v119, v120
	v_add_f32_e32 v118, v118, v80
	v_add_f32_e32 v80, v115, v121
	v_add_f32_e32 v119, v114, v80
	v_and_b32_e32 v80, 0xffff0000, v81
	v_lshlrev_b32_e32 v81, 16, v81
	v_pk_mul_f32 v[114:115], v[92:93], v[80:81]
	v_pk_mul_f32 v[80:81], v[102:103], v[80:81]
	v_add_f32_e32 v115, v115, v118
	v_add_f32_e32 v81, v81, v119
	v_add_f32_e32 v119, v80, v81
	v_and_b32_e32 v80, 0xffff0000, v82
	v_lshlrev_b32_e32 v81, 16, v82
	v_add_f32_e32 v118, v114, v115
	v_pk_mul_f32 v[114:115], v[90:91], v[80:81]
	v_pk_mul_f32 v[80:81], v[100:101], v[80:81]
	v_add_f32_e32 v82, v115, v118
	v_add_f32_e32 v81, v81, v119
	v_add_f32_e32 v115, v80, v81
	v_and_b32_e32 v80, 0xffff0000, v83
	v_lshlrev_b32_e32 v81, 16, v83
	v_add_f32_e32 v114, v114, v82
	v_pk_mul_f32 v[82:83], v[88:89], v[80:81]
	v_pk_mul_f32 v[80:81], v[94:95], v[80:81]
	v_add_f32_e32 v83, v83, v114
	v_add_f32_e32 v82, v82, v83
	v_add_f32_e32 v81, v81, v115
	v_add_f32_e32 v114, v80, v81
	v_mul_f32_e64 v80, |v82|, s2
	v_exp_f32_e32 v80, v80
	v_min_f32_e32 v81, 0, v82
	v_add_f32_e32 v80, 1.0, v80
	v_cmp_gt_f32_e32 vcc, s0, v80
	s_nop 1
	v_cndmask_b32_e64 v82, 0, 32, vcc
	v_ldexp_f32 v80, v80, v82
	v_log_f32_e32 v80, v80
	s_nop 0
	v_mul_f32_e32 v82, 0x3f317217, v80
	v_fma_f32 v82, v80, s3, -v82
	v_fmac_f32_e32 v82, 0x3377d1cf, v80
	v_fmac_f32_e32 v82, 0x3f317217, v80
	v_cmp_lt_f32_e64 s[14:15], |v80|, s4
	s_nop 1
	v_cndmask_b32_e64 v80, v80, v82, s[14:15]
	v_cndmask_b32_e32 v82, 0, v222, vcc
	v_sub_f32_e32 v83, v80, v82
	v_mul_f32_e64 v82, |v114|, s2
	v_exp_f32_e32 v82, v82
	v_min_f32_e32 v80, 0, v114
	v_add_f32_e32 v82, 1.0, v82
	v_cmp_gt_f32_e32 vcc, s0, v82
	s_mov_b32 s0, 0x3d800000
	s_nop 0
	v_cndmask_b32_e64 v114, 0, 32, vcc
	v_ldexp_f32 v82, v82, v114
	v_log_f32_e32 v82, v82
	s_nop 0
	v_mul_f32_e32 v114, 0x3f317217, v82
	v_fma_f32 v114, v82, s3, -v114
	v_fmac_f32_e32 v114, 0x3377d1cf, v82
	v_fmac_f32_e32 v114, 0x3f317217, v82
	v_cmp_lt_f32_e64 s[14:15], |v82|, s4
	s_nop 1
	v_cndmask_b32_e64 v82, v82, v114, s[14:15]
	v_cndmask_b32_e32 v114, 0, v222, vcc
	v_sub_f32_e32 v82, v82, v114
	v_pk_add_f32 v[80:81], v[80:81], v[82:83] neg_lo:[0,1] neg_hi:[0,1]
	s_nop 0
	v_pk_mul_f32 v[114:115], v[80:81], s[0:1] op_sel_hi:[1,0]
.LBB0_897:
	v_mov_b32_e32 v118, 0
	s_and_b64 vcc, exec, s[12:13]
	v_mov_b32_e32 v120, 0
	v_mov_b32_e32 v121, 0
	s_cbranch_vccnz .LBB0_899
	s_add_i32 s0, s48, s46
	s_mul_hi_i32 s3, s0, 0x1600
	s_mulk_i32 s0, 0x1600
	s_add_u32 s2, s30, s0
	s_addc_u32 s3, s31, s3
	s_add_u32 s4, s2, 0x1400
	s_addc_u32 s5, s3, 0
	s_mov_b32 s2, 0xbfb8aa3b
	s_mov_b32 s0, 0x800000
	s_mov_b32 s3, 0x3f317217
	s_mov_b32 s4, 0x7f800000
	s_waitcnt vmcnt(0)
	v_readlane_b32 s72, v193, 48
	v_readlane_b32 s73, v193, 49
	v_readlane_b32 s74, v193, 50
	v_readlane_b32 s75, v193, 51
	v_readlane_b32 s76, v193, 52
	v_readlane_b32 s77, v193, 53
	v_readlane_b32 s78, v193, 54
	v_readlane_b32 s79, v193, 55
	v_mov_b32_e32 v188, s72
	v_mov_b32_e32 v189, s73
	v_mov_b32_e32 v190, s74
	v_mov_b32_e32 v191, s75
	v_mov_b32_e32 v80, s76
	v_mov_b32_e32 v81, s77
	v_mov_b32_e32 v82, s78
	v_mov_b32_e32 v83, s79
	v_lshlrev_b32_e32 v119, 16, v188
	v_and_b32_e32 v120, 0xffff0000, v188
	v_lshlrev_b32_e32 v121, 16, v189
	v_and_b32_e32 v187, 0xffff0000, v189
	v_lshlrev_b32_e32 v188, 16, v190
	v_and_b32_e32 v189, 0xffff0000, v190
	v_fma_f32 v190, v176, v119, v177
	v_fma_f32 v119, v182, v119, v186
	v_fmac_f32_e32 v190, v175, v120
	v_fmac_f32_e32 v119, v181, v120
	v_fmac_f32_e32 v190, v174, v121
	v_fmac_f32_e32 v119, v180, v121
	v_fmac_f32_e32 v190, v173, v187
	v_fmac_f32_e32 v119, v185, v187
	v_fmac_f32_e32 v190, v179, v188
	v_fmac_f32_e32 v119, v184, v188
	v_and_b32_e32 v120, 0xffff0000, v191
	v_lshlrev_b32_e32 v121, 16, v191
	v_fmac_f32_e32 v190, v178, v189
	v_fmac_f32_e32 v119, v183, v189
	v_pk_mul_f32 v[188:189], v[98:99], v[120:121]
	v_pk_mul_f32 v[120:121], v[106:107], v[120:121]
	v_add_f32_e32 v187, v189, v190
	v_add_f32_e32 v119, v121, v119
	v_add_f32_e32 v119, v120, v119
	v_and_b32_e32 v120, 0xffff0000, v80
	v_lshlrev_b32_e32 v121, 16, v80
	v_add_f32_e32 v187, v188, v187
	v_pk_mul_f32 v[188:189], v[96:97], v[120:121]
	v_pk_mul_f32 v[120:121], v[104:105], v[120:121]
	v_add_f32_e32 v80, v189, v187
	v_add_f32_e32 v187, v188, v80
	v_add_f32_e32 v80, v121, v119
	v_add_f32_e32 v119, v120, v80
	v_and_b32_e32 v80, 0xffff0000, v81
	v_lshlrev_b32_e32 v81, 16, v81
	v_pk_mul_f32 v[120:121], v[92:93], v[80:81]
	v_pk_mul_f32 v[80:81], v[102:103], v[80:81]
	v_add_f32_e32 v121, v121, v187
	v_add_f32_e32 v81, v81, v119
	v_add_f32_e32 v119, v80, v81
	v_and_b32_e32 v80, 0xffff0000, v82
	v_lshlrev_b32_e32 v81, 16, v82
	v_add_f32_e32 v187, v120, v121
	v_pk_mul_f32 v[120:121], v[90:91], v[80:81]
	v_pk_mul_f32 v[80:81], v[100:101], v[80:81]
	v_add_f32_e32 v82, v121, v187
	v_add_f32_e32 v81, v81, v119
	v_add_f32_e32 v119, v80, v81
	v_and_b32_e32 v80, 0xffff0000, v83
	v_lshlrev_b32_e32 v81, 16, v83
	v_add_f32_e32 v120, v120, v82
	v_pk_mul_f32 v[82:83], v[88:89], v[80:81]
	v_pk_mul_f32 v[80:81], v[94:95], v[80:81]
	v_add_f32_e32 v83, v83, v120
	v_add_f32_e32 v82, v82, v83
	v_add_f32_e32 v81, v81, v119
	v_add_f32_e32 v119, v80, v81
	v_mul_f32_e64 v80, |v82|, s2
	v_exp_f32_e32 v80, v80
	v_min_f32_e32 v81, 0, v82
	v_add_f32_e32 v80, 1.0, v80
	v_cmp_gt_f32_e32 vcc, s0, v80
	s_nop 1
	v_cndmask_b32_e64 v82, 0, 32, vcc
	v_ldexp_f32 v80, v80, v82
	v_log_f32_e32 v80, v80
	s_nop 0
	v_mul_f32_e32 v82, 0x3f317217, v80
	v_fma_f32 v82, v80, s3, -v82
	v_fmac_f32_e32 v82, 0x3377d1cf, v80
	v_fmac_f32_e32 v82, 0x3f317217, v80
	v_cmp_lt_f32_e64 s[12:13], |v80|, s4
	s_nop 1
	v_cndmask_b32_e64 v80, v80, v82, s[12:13]
	v_cndmask_b32_e32 v82, 0, v222, vcc
	v_sub_f32_e32 v83, v80, v82
	v_mul_f32_e64 v82, |v119|, s2
	v_exp_f32_e32 v82, v82
	v_min_f32_e32 v80, 0, v119
	v_add_f32_e32 v82, 1.0, v82
	v_cmp_gt_f32_e32 vcc, s0, v82
	s_mov_b32 s0, 0x3d800000
	s_nop 0
	v_cndmask_b32_e64 v119, 0, 32, vcc
	v_ldexp_f32 v82, v82, v119
	v_log_f32_e32 v82, v82
	s_nop 0
	v_mul_f32_e32 v119, 0x3f317217, v82
	v_fma_f32 v119, v82, s3, -v119
	v_fmac_f32_e32 v119, 0x3377d1cf, v82
	v_fmac_f32_e32 v119, 0x3f317217, v82
	v_cmp_lt_f32_e64 s[12:13], |v82|, s4
	s_nop 1
	v_cndmask_b32_e64 v82, v82, v119, s[12:13]
	v_cndmask_b32_e32 v119, 0, v222, vcc
	v_sub_f32_e32 v82, v82, v119
	v_pk_add_f32 v[80:81], v[80:81], v[82:83] neg_lo:[0,1] neg_hi:[0,1]
	s_nop 0
	v_pk_mul_f32 v[120:121], v[80:81], s[0:1] op_sel_hi:[1,0]
; DI float bf2f(unsigned v) { return __uint_as_float(v << 16); }
; template <bool FINAL>
; DI void gla_unit(KA a, int l, int item, LAS unsigned char* lds) {
;     ...
;             for (int it = 0; it < 4; ++it) {
;                 const int idx = it * 512 + tid; sv[hh][it] = (f32x4){0.f, 0.f, 0.f, 0.f};
;                 if (S0[hh]) sv[hh][it] = *(const f32x4*)(S0[hh] + (idx >> 5) * 128 + (idx & 31) * 4);
;                 else if (Sb) { const u32x2 v = *(const u32x2*)(Sb + (idx >> 5) * 128 + (idx & 31) * 4); sv[hh][it] = (f32x4){bf2f(v.x & 0xffffu), __uint_as_float(v.x & 0xffff0000u), bf2f(v.y & 0xffffu), __uint_as_float(v.y & 0xffff0000u)}; }
;             }
;     ...
;         for (int jj = 0; jj < 8; ++jj) {
;             const int t = 8 * tg + jj;
;             float ga = 0.f, gb = 0.f;
;             if (t < nvalid) {
;                 const u32x4* lp = (const u32x4*)(U + (size_t)(row0 + t) * UN + U_LR);
;                 float lr[16]; unpack8(lp[0], lr); unpack8(lp[1], lr + 8);
;                 float za = bg[0], zb = bg[1];
; #pragma unroll
;                 for (int e = 0; e < 16; ++e) { za += wg[0][e] * lr[e]; zb += wg[1][e] * lr[e]; }
;                 ga = (fminf(za, 0.f) - __logf(1.f + __expf(-fabsf(za)))) * (1.f / 16.f);
;                 gb = (fminf(zb, 0.f) - __logf(1.f + __expf(-fabsf(zb)))) * (1.f / 16.f);
;             }
;             run0 += ga; run1 += gb; bl[0][jj] = run0; bl[1][jj] = run1;
;         }
.LBB0_899:
	s_and_b64 vcc, exec, s[10:11]
	v_mov_b32_e32 v119, 0
	s_cbranch_vccnz .LBB0_901
	s_add_i32 s0, s47, s46
	s_mul_hi_i32 s3, s0, 0x1600
	s_mulk_i32 s0, 0x1600
	s_add_u32 s2, s30, s0
	s_addc_u32 s3, s31, s3
	s_add_u32 s4, s2, 0x1400
	s_addc_u32 s5, s3, 0
	s_mov_b32 s2, 0xbfb8aa3b
	s_mov_b32 s0, 0x800000
	s_mov_b32 s3, 0x3f317217
	s_mov_b32 s4, 0x7f800000
	s_waitcnt vmcnt(0)
	v_readlane_b32 s72, v193, 56
	v_readlane_b32 s73, v193, 57
	v_readlane_b32 s74, v193, 58
	v_readlane_b32 s75, v193, 59
	v_readlane_b32 s76, v193, 60
	v_readlane_b32 s77, v193, 61
	v_readlane_b32 s78, v193, 62
	v_readlane_b32 s79, v193, 63
	v_mov_b32_e32 v188, s72
	v_mov_b32_e32 v189, s73
	v_mov_b32_e32 v190, s74
	v_mov_b32_e32 v191, s75
	v_mov_b32_e32 v80, s76
	v_mov_b32_e32 v81, s77
	v_mov_b32_e32 v82, s78
	v_mov_b32_e32 v83, s79
	v_lshlrev_b32_e32 v118, 16, v188
	v_and_b32_e32 v119, 0xffff0000, v188
	v_fmac_f32_e32 v177, v176, v118
	v_lshlrev_b32_e32 v187, 16, v189
	v_fmac_f32_e32 v177, v175, v119
	v_and_b32_e32 v188, 0xffff0000, v189
	v_fmac_f32_e32 v186, v182, v118
	v_fmac_f32_e32 v177, v174, v187
	v_lshlrev_b32_e32 v189, 16, v190
	v_fmac_f32_e32 v186, v181, v119
	v_fmac_f32_e32 v177, v173, v188
	v_and_b32_e32 v190, 0xffff0000, v190
	v_fmac_f32_e32 v186, v180, v187
	v_fmac_f32_e32 v177, v179, v189
	v_and_b32_e32 v118, 0xffff0000, v191
	v_lshlrev_b32_e32 v119, 16, v191
	v_fmac_f32_e32 v186, v185, v188
	v_fmac_f32_e32 v177, v178, v190
	v_pk_mul_f32 v[98:99], v[98:99], v[118:119]
	v_fmac_f32_e32 v186, v184, v189
	v_add_f32_e32 v99, v99, v177
	v_fmac_f32_e32 v186, v183, v190
	v_add_f32_e32 v173, v98, v99
	v_pk_mul_f32 v[98:99], v[106:107], v[118:119]
	s_nop 0
	v_add_f32_e32 v99, v99, v186
	v_add_f32_e32 v106, v98, v99
	v_and_b32_e32 v98, 0xffff0000, v80
	v_lshlrev_b32_e32 v99, 16, v80
	v_pk_mul_f32 v[96:97], v[96:97], v[98:99]
	s_nop 0
	v_add_f32_e32 v80, v97, v173
	v_add_f32_e32 v107, v96, v80
	v_pk_mul_f32 v[96:97], v[104:105], v[98:99]
	s_nop 0
	v_add_f32_e32 v80, v97, v106
	v_add_f32_e32 v96, v96, v80
	v_and_b32_e32 v80, 0xffff0000, v81
	v_lshlrev_b32_e32 v81, 16, v81
	v_pk_mul_f32 v[92:93], v[92:93], v[80:81]
	v_pk_mul_f32 v[80:81], v[102:103], v[80:81]
	v_add_f32_e32 v93, v93, v107
	v_add_f32_e32 v81, v81, v96
	v_add_f32_e32 v92, v92, v93
	v_add_f32_e32 v93, v80, v81
	v_and_b32_e32 v80, 0xffff0000, v82
	v_lshlrev_b32_e32 v81, 16, v82
	v_pk_mul_f32 v[90:91], v[90:91], v[80:81]
	v_pk_mul_f32 v[80:81], v[100:101], v[80:81]
	v_add_f32_e32 v82, v91, v92
	v_add_f32_e32 v81, v81, v93
	v_add_f32_e32 v91, v80, v81
	v_and_b32_e32 v80, 0xffff0000, v83
	v_lshlrev_b32_e32 v81, 16, v83
	v_add_f32_e32 v90, v90, v82
	v_pk_mul_f32 v[82:83], v[88:89], v[80:81]
	v_pk_mul_f32 v[80:81], v[94:95], v[80:81]
	v_add_f32_e32 v83, v83, v90
	v_add_f32_e32 v82, v82, v83
	v_add_f32_e32 v81, v81, v91
	v_add_f32_e32 v88, v80, v81
	v_mul_f32_e64 v80, |v82|, s2
	v_exp_f32_e32 v80, v80
	v_min_f32_e32 v81, 0, v82
	v_add_f32_e32 v80, 1.0, v80
	v_cmp_gt_f32_e32 vcc, s0, v80
	s_nop 1
	v_cndmask_b32_e64 v82, 0, 32, vcc
	v_ldexp_f32 v80, v80, v82
	v_log_f32_e32 v80, v80
	s_nop 0
	v_mul_f32_e32 v82, 0x3f317217, v80
	v_fma_f32 v82, v80, s3, -v82
	v_fmac_f32_e32 v82, 0x3377d1cf, v80
	v_fmac_f32_e32 v82, 0x3f317217, v80
	v_cmp_lt_f32_e64 s[10:11], |v80|, s4
	s_nop 1
	v_cndmask_b32_e64 v80, v80, v82, s[10:11]
	v_cndmask_b32_e32 v82, 0, v222, vcc
	v_sub_f32_e32 v83, v80, v82
	v_mul_f32_e64 v82, |v88|, s2
	v_exp_f32_e32 v82, v82
	v_min_f32_e32 v80, 0, v88
	v_add_f32_e32 v82, 1.0, v82
	v_cmp_gt_f32_e32 vcc, s0, v82
	s_mov_b32 s0, 0x3d800000
	s_nop 0
	v_cndmask_b32_e64 v88, 0, 32, vcc
	v_ldexp_f32 v82, v82, v88
	v_log_f32_e32 v82, v82
	s_nop 0
	v_mul_f32_e32 v88, 0x3f317217, v82
	v_fma_f32 v88, v82, s3, -v88
	v_fmac_f32_e32 v88, 0x3377d1cf, v82
	v_fmac_f32_e32 v88, 0x3f317217, v82
	v_cmp_lt_f32_e64 s[10:11], |v82|, s4
	s_nop 1
	v_cndmask_b32_e64 v82, v82, v88, s[10:11]
	v_cndmask_b32_e32 v88, 0, v222, vcc
	v_sub_f32_e32 v82, v82, v88
	v_pk_add_f32 v[80:81], v[80:81], v[82:83] neg_lo:[0,1] neg_hi:[0,1]
	s_nop 0
	v_pk_mul_f32 v[118:119], v[80:81], s[0:1] op_sel_hi:[1,0]
.LBB0_901:
	s_waitcnt vmcnt(0)
	v_mul_f32_e32 v140, 0x3e000000, v140
	v_mul_f32_e32 v136, 0x3e000000, v136
	v_mul_f32_e32 v138, 0x3e000000, v138
	v_mul_f32_e32 v132, 0x3e000000, v132
	v_mul_f32_e32 v135, 0x3e000000, v135
	v_mul_f32_e32 v128, 0x3e000000, v128
	v_mul_f32_e32 v131, 0x3e000000, v131
	v_mul_f32_e32 v125, 0x3e000000, v125
	v_mul_f32_e32 v154, 0x3e000000, v154
	v_mul_f32_e32 v141, 0x3e000000, v141
	v_mul_f32_e32 v157, 0x3e000000, v157
	v_mul_f32_e32 v143, 0x3e000000, v143
	v_mul_f32_e32 v161, 0x3e000000, v161
	v_mul_f32_e32 v159, 0x3e000000, v159
	v_mul_f32_e32 v165, 0x3e000000, v165
	v_mul_f32_e32 v163, 0x3e000000, v163
	s_andn2_b64 vcc, exec, s[66:67]
	s_cbranch_vccnz .Lm3_nu0
	v_lshlrev_b32_e32 v8, 16, v10
	v_and_b32_e32 v9, 0xffff0000, v10
	v_lshlrev_b32_e32 v10, 16, v11
	v_and_b32_e32 v11, 0xffff0000, v11
	v_lshlrev_b32_e32 v12, 16, v14
	v_and_b32_e32 v13, 0xffff0000, v14
	v_lshlrev_b32_e32 v14, 16, v15
	v_and_b32_e32 v15, 0xffff0000, v15
	v_lshlrev_b32_e32 v16, 16, v18
	v_and_b32_e32 v17, 0xffff0000, v18
	v_lshlrev_b32_e32 v18, 16, v19
	v_and_b32_e32 v19, 0xffff0000, v19
	v_lshlrev_b32_e32 v20, 16, v22
	v_and_b32_e32 v21, 0xffff0000, v22
	v_lshlrev_b32_e32 v22, 16, v23
	v_and_b32_e32 v23, 0xffff0000, v23
.Lm3_nu0:
	s_andn2_b64 vcc, exec, s[68:69]
	s_cbranch_vccnz .Lm3_nu1
	v_lshlrev_b32_e32 v64, 16, v66
	v_and_b32_e32 v65, 0xffff0000, v66
	v_lshlrev_b32_e32 v66, 16, v67
	v_and_b32_e32 v67, 0xffff0000, v67
	v_lshlrev_b32_e32 v68, 16, v70
	v_and_b32_e32 v69, 0xffff0000, v70
	v_lshlrev_b32_e32 v70, 16, v71
	v_and_b32_e32 v71, 0xffff0000, v71
	v_lshlrev_b32_e32 v72, 16, v74
	v_and_b32_e32 v73, 0xffff0000, v74
	v_lshlrev_b32_e32 v74, 16, v75
	v_and_b32_e32 v75, 0xffff0000, v75
	v_lshlrev_b32_e32 v76, 16, v78
	v_and_b32_e32 v77, 0xffff0000, v78
	v_lshlrev_b32_e32 v78, 16, v79
	v_and_b32_e32 v79, 0xffff0000, v79
